# P5 SwiGLU epilogue: the 8 per-row scale loads issued together (one wait) instead of load/wait/store-drain per row
# speedup vs baseline: 1.0219x; 1.0040x over previous
; __device__ __forceinline__ unsigned cvt_pk_bf16(float lo, float hi) { unsigned r; asm volatile("v_cvt_pk_bf16_f32 %0, %1, %2" : "=v"(r) : "v"(lo), "v"(hi)); return r; }
; __device__ __forceinline__ float silu_f(float x) { return x * __builtin_amdgcn_rcpf(1.0f + __builtin_amdgcn_exp2f(-1.4426950408889634f * x)); }
;     static __device__ __forceinline__ f32x4 deq(const f32x4 a, const float sa, const f32x4 cm) { if constexpr (!Q) return a; else { const i32x4 i = __builtin_bit_cast(i32x4, a); return (f32x4){(float)i[0] * (sa * cm[0]), (float)i[1] * (sa * cm[1]), (float)i[2] * (sa * cm[2]), (float)i[3] * (sa * cm[ ...
;     __device__ __forceinline__ void operator()(const f32x4 (&acc)[2][2][4][2], const Unit& u, int wr, int wc, int fr, int fq) const {
;     ...
; #pragma unroll
;         for (int ai = 0; ai < 2; ++ai)
; #pragma unroll
;             for (int m = 0; m < 4; ++m) { bf16_t* rowp = (bf16_t*)((unsigned char*)O + (size_t)(row0 + ai * HALF + m * 16) * HROWB) + col0;
;                 float sa = 1.f; if constexpr (Q) sa = SA[row0 + ai * HALF + m * 16];
;                     const f32x4 g0 = deq(acc[ai][0][m][0], sa, cg0), g1 = deq(acc[ai][0][m][1], sa, cg1), u0 = deq(acc[ai][1][m][0], sa, cu0), u1 = deq(acc[ai][1][m][1], sa, cu1);
;                 f32x4 v0, v1;
; #pragma unroll
;                 for (int j = 0; j < 4; ++j) { v0[j] = silu_f(g0[j]) * u0[j]; v1[j] = silu_f(g1[j]) * u1[j]; }
;                 u32x4 w; w.x = cvt_pk_bf16(v0[0], v0[1]); w.y = cvt_pk_bf16(v0[2], v0[3]); w.z = cvt_pk_bf16(v1[0], v1[1]); w.w = cvt_pk_bf16(v1[2], v1[3]);
;                 *(u32x4*)rowp = w; }
.LBB0_558:
	global_load_dword v220, v[158:159], off
	global_load_dword v221, v[158:159], off offset:64
	global_load_dword v222, v[158:159], off offset:128
	global_load_dword v223, v[158:159], off offset:192
	global_load_dword v224, v[158:159], off offset:512
	global_load_dword v225, v[158:159], off offset:576
	global_load_dword v226, v[158:159], off offset:640
	global_load_dword v227, v[158:159], off offset:704
	s_waitcnt vmcnt(0)
	v_mov_b32_e32 v102, v220
	v_mov_b32_e32 v74, v60
	v_mov_b32_e32 v75, v32
	v_pk_mul_f32 v[92:93], v[74:75], v[102:103] op_sel_hi:[1,0]
	s_nop 0
	v_pk_mul_f32 v[186:187], v[92:93], v[174:175]
	v_mov_b32_e32 v92, v61
	v_mov_b32_e32 v93, v33
	v_mul_f32_e32 v67, 0xbfb8aa3b, v187
	v_pk_mul_f32 v[94:95], v[92:93], v[102:103] op_sel_hi:[1,0]
	v_exp_f32_e32 v67, v67
	v_pk_mul_f32 v[188:189], v[94:95], v[172:173]
	v_mov_b32_e32 v94, v62
	v_mov_b32_e32 v95, v34
	v_pk_mul_f32 v[110:111], v[94:95], v[102:103] op_sel_hi:[1,0]
	v_add_f32_e32 v67, 1.0, v67
	v_pk_mul_f32 v[190:191], v[110:111], v[170:171]
	v_mov_b32_e32 v110, v63
	v_mov_b32_e32 v111, v35
	v_pk_mul_f32 v[178:179], v[110:111], v[102:103] op_sel_hi:[1,0]
	v_rcp_f32_e32 v67, v67
	v_pk_mul_f32 v[194:195], v[178:179], v[168:169]
	v_mov_b32_e32 v178, v56
	v_mov_b32_e32 v179, v20
	v_pk_mul_f32 v[180:181], v[178:179], v[102:103] op_sel_hi:[1,0]
	v_mul_f32_e32 v67, v187, v67
	v_pk_mul_f32 v[196:197], v[180:181], v[166:167]
	v_mov_b32_e32 v180, v57
	v_mov_b32_e32 v181, v21
	v_pk_mul_f32 v[182:183], v[180:181], v[102:103] op_sel_hi:[1,0]
	v_mul_f32_e32 v67, v186, v67
	v_pk_mul_f32 v[200:201], v[182:183], v[164:165]
	v_mul_f32_e32 v143, 0xbfb8aa3b, v189
	v_mul_f32_e32 v186, 0xbfb8aa3b, v201
	v_exp_f32_e32 v143, v143
	v_exp_f32_e32 v186, v186
	v_mov_b32_e32 v182, v58
	v_mov_b32_e32 v183, v22
	v_add_f32_e32 v143, 1.0, v143
	v_add_f32_e32 v186, 1.0, v186
	v_rcp_f32_e32 v143, v143
	v_rcp_f32_e32 v186, v186
	v_pk_mul_f32 v[184:185], v[182:183], v[102:103] op_sel_hi:[1,0]
	v_mul_f32_e32 v73, 0xbfb8aa3b, v197
	v_mul_f32_e32 v143, v189, v143
	v_mul_f32_e32 v186, v201, v186
	v_mul_f32_e32 v143, v188, v143
	v_mul_f32_e32 v188, v200, v186
	v_mul_f32_e32 v186, 0xbfb8aa3b, v191
	v_exp_f32_e32 v186, v186
	v_pk_mul_f32 v[202:203], v[184:185], v[162:163]
	v_mov_b32_e32 v184, v59
	v_mov_b32_e32 v185, v23
	v_add_f32_e32 v186, 1.0, v186
	v_rcp_f32_e32 v186, v186
	v_pk_mul_f32 v[102:103], v[184:185], v[102:103] op_sel_hi:[1,0]
	v_exp_f32_e32 v73, v73
	v_pk_mul_f32 v[102:103], v[102:103], v[160:161]
	v_mul_f32_e32 v186, v191, v186
	v_mul_f32_e32 v187, v190, v186
	v_mul_f32_e32 v186, 0xbfb8aa3b, v203
	v_exp_f32_e32 v186, v186
	v_add_f32_e32 v73, 1.0, v73
	v_rcp_f32_e32 v73, v73
	v_add_f32_e32 v186, 1.0, v186
	v_rcp_f32_e32 v186, v186
	v_mul_f32_e32 v73, v197, v73
	v_mul_f32_e32 v73, v196, v73
	v_mul_f32_e32 v186, v203, v186
	v_mul_f32_e32 v189, v202, v186
	v_mul_f32_e32 v186, 0xbfb8aa3b, v195
	v_exp_f32_e32 v186, v186
	s_nop 0
	v_add_f32_e32 v186, 1.0, v186
	v_rcp_f32_e32 v186, v186
	s_nop 0
	v_mul_f32_e32 v186, v195, v186
	v_mul_f32_e32 v194, v194, v186
	v_mul_f32_e32 v186, 0xbfb8aa3b, v103
	v_exp_f32_e32 v186, v186
	s_nop 0
	v_add_f32_e32 v186, 1.0, v186
	v_rcp_f32_e32 v186, v186
	s_nop 0
	v_mul_f32_e32 v103, v103, v186
	v_mul_f32_e32 v195, v102, v103
	v_lshlrev_b64 v[102:103], 1, v[156:157]
	v_lshl_add_u64 v[190:191], v[176:177], 0, v[102:103]
	v_cvt_pk_bf16_f32 v186, v67, v143
	v_ashrrev_i32_e32 v143, 31, v142
	v_cvt_pk_bf16_f32 v187, v187, v194
	v_cvt_pk_bf16_f32 v188, v73, v188
	v_cvt_pk_bf16_f32 v189, v189, v195
	global_store_dwordx4 v[190:191], v[186:189], off
	v_lshl_add_u64 v[190:191], v[142:143], 2, s[92:93]
	v_mov_b32_e32 v190, v221
	v_mov_b64_e32 v[186:187], s[82:83]
	v_mad_i64_i32 v[188:189], s[4:5], v142, s86, v[186:187]
	s_nop 0
	v_pk_mul_f32 v[194:195], v[74:75], v[190:191] op_sel_hi:[1,0]
	s_nop 0
	v_pk_mul_f32 v[194:195], v[194:195], v[140:141]
	v_pk_mul_f32 v[196:197], v[92:93], v[190:191] op_sel_hi:[1,0]
	v_mul_f32_e32 v67, 0xbfb8aa3b, v195
	v_exp_f32_e32 v67, v67
	v_pk_mul_f32 v[206:207], v[180:181], v[190:191] op_sel_hi:[1,0]
	v_pk_mul_f32 v[196:197], v[196:197], v[138:139]
	v_pk_mul_f32 v[206:207], v[206:207], v[130:131]
	v_add_f32_e32 v67, 1.0, v67
	v_rcp_f32_e32 v67, v67
	v_mul_f32_e32 v143, 0xbfb8aa3b, v197
	v_exp_f32_e32 v143, v143
	v_pk_mul_f32 v[200:201], v[94:95], v[190:191] op_sel_hi:[1,0]
	v_mul_f32_e32 v67, v195, v67
	v_mul_f32_e32 v67, v194, v67
	v_mul_f32_e32 v194, 0xbfb8aa3b, v207
	v_exp_f32_e32 v194, v194
	v_add_f32_e32 v143, 1.0, v143
	v_rcp_f32_e32 v143, v143
	v_pk_mul_f32 v[200:201], v[200:201], v[136:137]
	v_add_f32_e32 v194, 1.0, v194
	v_rcp_f32_e32 v194, v194
	v_mul_f32_e32 v143, v197, v143
	v_mul_f32_e32 v143, v196, v143
	v_pk_mul_f32 v[208:209], v[182:183], v[190:191] op_sel_hi:[1,0]
	v_mul_f32_e32 v194, v207, v194
	v_mul_f32_e32 v196, v206, v194
	v_mul_f32_e32 v194, 0xbfb8aa3b, v201
	v_exp_f32_e32 v194, v194
	v_pk_mul_f32 v[208:209], v[208:209], v[128:129]
	v_pk_mul_f32 v[202:203], v[110:111], v[190:191] op_sel_hi:[1,0]
	v_pk_mul_f32 v[204:205], v[178:179], v[190:191] op_sel_hi:[1,0]
	v_add_f32_e32 v194, 1.0, v194
	v_rcp_f32_e32 v194, v194
	v_pk_mul_f32 v[202:203], v[202:203], v[134:135]
	v_pk_mul_f32 v[190:191], v[184:185], v[190:191] op_sel_hi:[1,0]
	v_pk_mul_f32 v[204:205], v[204:205], v[132:133]
	v_mul_f32_e32 v194, v201, v194
	v_mul_f32_e32 v197, v200, v194
	v_mul_f32_e32 v194, 0xbfb8aa3b, v209
	v_exp_f32_e32 v194, v194
	v_pk_mul_f32 v[190:191], v[190:191], v[126:127]
	v_mul_f32_e32 v73, 0xbfb8aa3b, v205
	v_exp_f32_e32 v73, v73
	v_add_f32_e32 v194, 1.0, v194
	v_rcp_f32_e32 v194, v194
	v_add_f32_e32 v73, 1.0, v73
	v_rcp_f32_e32 v73, v73
; __device__ __forceinline__ unsigned cvt_pk_bf16(float lo, float hi) { unsigned r; asm volatile("v_cvt_pk_bf16_f32 %0, %1, %2" : "=v"(r) : "v"(lo), "v"(hi)); return r; }
; __device__ __forceinline__ float silu_f(float x) { return x * __builtin_amdgcn_rcpf(1.0f + __builtin_amdgcn_exp2f(-1.4426950408889634f * x)); }
;     static __device__ __forceinline__ f32x4 deq(const f32x4 a, const float sa, const f32x4 cm) { if constexpr (!Q) return a; else { const i32x4 i = __builtin_bit_cast(i32x4, a); return (f32x4){(float)i[0] * (sa * cm[0]), (float)i[1] * (sa * cm[1]), (float)i[2] * (sa * cm[2]), (float)i[3] * (sa * cm[ ...
;     __device__ __forceinline__ void operator()(const f32x4 (&acc)[2][2][4][2], const Unit& u, int wr, int wc, int fr, int fq) const {
;     ...
;         for (int ai = 0; ai < 2; ++ai)
; #pragma unroll
;             for (int m = 0; m < 4; ++m) { bf16_t* rowp = (bf16_t*)((unsigned char*)O + (size_t)(row0 + ai * HALF + m * 16) * HROWB) + col0;
;                 float sa = 1.f; if constexpr (Q) sa = SA[row0 + ai * HALF + m * 16];
;                     const f32x4 g0 = deq(acc[ai][0][m][0], sa, cg0), g1 = deq(acc[ai][0][m][1], sa, cg1), u0 = deq(acc[ai][1][m][0], sa, cu0), u1 = deq(acc[ai][1][m][1], sa, cu1);
;                 f32x4 v0, v1;
; #pragma unroll
;                 for (int j = 0; j < 4; ++j) { v0[j] = silu_f(g0[j]) * u0[j]; v1[j] = silu_f(g1[j]) * u1[j]; }
;                 u32x4 w; w.x = cvt_pk_bf16(v0[0], v0[1]); w.y = cvt_pk_bf16(v0[2], v0[3]); w.z = cvt_pk_bf16(v1[0], v1[1]); w.w = cvt_pk_bf16(v1[2], v1[3]);
;                 *(u32x4*)rowp = w; }
	v_mul_f32_e32 v194, v209, v194
	v_mul_f32_e32 v200, v208, v194
	v_mul_f32_e32 v194, 0xbfb8aa3b, v203
	v_exp_f32_e32 v194, v194
	v_mul_f32_e32 v73, v205, v73
	v_mul_f32_e32 v73, v204, v73
	v_add_f32_e32 v194, 1.0, v194
	v_rcp_f32_e32 v194, v194
	s_nop 0
	v_mul_f32_e32 v194, v203, v194
	v_mul_f32_e32 v201, v202, v194
	v_mul_f32_e32 v194, 0xbfb8aa3b, v191
	v_exp_f32_e32 v194, v194
	s_nop 0
	v_add_f32_e32 v194, 1.0, v194
	v_rcp_f32_e32 v194, v194
	s_nop 0
	v_mul_f32_e32 v191, v191, v194
	v_mul_f32_e32 v191, v190, v191
	v_lshl_add_u64 v[194:195], v[188:189], 0, v[102:103]
	v_cvt_pk_bf16_f32 v188, v67, v143
	v_cvt_pk_bf16_f32 v189, v197, v201
	v_cvt_pk_bf16_f32 v190, v73, v196
	v_cvt_pk_bf16_f32 v191, v200, v191
	v_ashrrev_i32_e32 v73, 31, v72
	global_store_dwordx4 v[194:195], v[188:191], off
	s_nop 1
	v_lshl_add_u64 v[190:191], v[72:73], 2, s[92:93]
	v_mov_b32_e32 v190, v222
	v_mad_i64_i32 v[188:189], s[4:5], v72, s86, v[186:187]
	s_nop 0
	v_pk_mul_f32 v[194:195], v[74:75], v[190:191] op_sel_hi:[1,0]
	s_nop 0
	v_pk_mul_f32 v[194:195], v[194:195], v[124:125]
	v_pk_mul_f32 v[196:197], v[92:93], v[190:191] op_sel_hi:[1,0]
	v_mul_f32_e32 v67, 0xbfb8aa3b, v195
	v_exp_f32_e32 v67, v67
	v_pk_mul_f32 v[206:207], v[180:181], v[190:191] op_sel_hi:[1,0]
	v_pk_mul_f32 v[196:197], v[196:197], v[122:123]
	v_pk_mul_f32 v[206:207], v[206:207], v[114:115]
	v_add_f32_e32 v67, 1.0, v67
	v_rcp_f32_e32 v67, v67
	v_mul_f32_e32 v143, 0xbfb8aa3b, v197
	v_exp_f32_e32 v143, v143
	v_pk_mul_f32 v[200:201], v[94:95], v[190:191] op_sel_hi:[1,0]
	v_mul_f32_e32 v67, v195, v67
	v_mul_f32_e32 v67, v194, v67
	v_mul_f32_e32 v194, 0xbfb8aa3b, v207
	v_exp_f32_e32 v194, v194
	v_add_f32_e32 v143, 1.0, v143
	v_rcp_f32_e32 v143, v143
	v_pk_mul_f32 v[200:201], v[200:201], v[120:121]
	v_add_f32_e32 v194, 1.0, v194
	v_rcp_f32_e32 v194, v194
	v_mul_f32_e32 v143, v197, v143
	v_mul_f32_e32 v143, v196, v143
	v_pk_mul_f32 v[208:209], v[182:183], v[190:191] op_sel_hi:[1,0]
	v_mul_f32_e32 v194, v207, v194
	v_mul_f32_e32 v196, v206, v194
	v_mul_f32_e32 v194, 0xbfb8aa3b, v201
	v_exp_f32_e32 v194, v194
	v_pk_mul_f32 v[208:209], v[208:209], v[112:113]
	v_pk_mul_f32 v[202:203], v[110:111], v[190:191] op_sel_hi:[1,0]
	v_pk_mul_f32 v[204:205], v[178:179], v[190:191] op_sel_hi:[1,0]
	v_add_f32_e32 v194, 1.0, v194
	v_rcp_f32_e32 v194, v194
	v_pk_mul_f32 v[202:203], v[202:203], v[118:119]
	v_pk_mul_f32 v[190:191], v[184:185], v[190:191] op_sel_hi:[1,0]
	v_pk_mul_f32 v[204:205], v[204:205], v[116:117]
	v_mul_f32_e32 v194, v201, v194
	v_mul_f32_e32 v197, v200, v194
	v_mul_f32_e32 v194, 0xbfb8aa3b, v209
	v_exp_f32_e32 v194, v194
	v_pk_mul_f32 v[190:191], v[190:191], v[108:109]
	v_mul_f32_e32 v73, 0xbfb8aa3b, v205
	v_exp_f32_e32 v73, v73
	v_add_f32_e32 v194, 1.0, v194
	v_rcp_f32_e32 v194, v194
	v_add_f32_e32 v73, 1.0, v73
	v_rcp_f32_e32 v73, v73
	v_mul_f32_e32 v194, v209, v194
	v_mul_f32_e32 v200, v208, v194
	v_mul_f32_e32 v194, 0xbfb8aa3b, v203
	v_exp_f32_e32 v194, v194
	v_mul_f32_e32 v73, v205, v73
	v_mul_f32_e32 v73, v204, v73
	v_add_f32_e32 v194, 1.0, v194
	v_rcp_f32_e32 v194, v194
	s_nop 0
	v_mul_f32_e32 v194, v203, v194
	v_mul_f32_e32 v201, v202, v194
	v_mul_f32_e32 v194, 0xbfb8aa3b, v191
	v_exp_f32_e32 v194, v194
	s_nop 0
	v_add_f32_e32 v194, 1.0, v194
	v_rcp_f32_e32 v194, v194
	s_nop 0
	v_mul_f32_e32 v191, v191, v194
	v_mul_f32_e32 v191, v190, v191
	v_lshl_add_u64 v[194:195], v[188:189], 0, v[102:103]
	v_cvt_pk_bf16_f32 v188, v67, v143
	v_cvt_pk_bf16_f32 v189, v197, v201
	v_cvt_pk_bf16_f32 v190, v73, v196
	v_cvt_pk_bf16_f32 v191, v200, v191
	v_ashrrev_i32_e32 v67, 31, v66
	global_store_dwordx4 v[194:195], v[188:191], off
	s_nop 1
	v_lshl_add_u64 v[190:191], v[66:67], 2, s[92:93]
	v_mov_b32_e32 v190, v223
	v_mad_i64_i32 v[188:189], s[4:5], v66, s86, v[186:187]
	v_lshl_add_u64 v[188:189], v[188:189], 0, v[102:103]
	s_nop 0
	v_pk_mul_f32 v[194:195], v[74:75], v[190:191] op_sel_hi:[1,0]
	s_nop 0
	v_pk_mul_f32 v[194:195], v[194:195], v[106:107]
	v_pk_mul_f32 v[200:201], v[94:95], v[190:191] op_sel_hi:[1,0]
	v_mul_f32_e32 v67, 0xbfb8aa3b, v195
	v_exp_f32_e32 v67, v67
	v_pk_mul_f32 v[208:209], v[182:183], v[190:191] op_sel_hi:[1,0]
	v_pk_mul_f32 v[196:197], v[92:93], v[190:191] op_sel_hi:[1,0]
	v_pk_mul_f32 v[200:201], v[200:201], v[100:101]
	v_add_f32_e32 v67, 1.0, v67
	v_rcp_f32_e32 v67, v67
	v_pk_mul_f32 v[202:203], v[110:111], v[190:191] op_sel_hi:[1,0]
	v_pk_mul_f32 v[204:205], v[178:179], v[190:191] op_sel_hi:[1,0]
	v_pk_mul_f32 v[206:207], v[180:181], v[190:191] op_sel_hi:[1,0]
	v_pk_mul_f32 v[208:209], v[208:209], v[88:89]
	v_pk_mul_f32 v[190:191], v[184:185], v[190:191] op_sel_hi:[1,0]
	v_mul_f32_e32 v67, v195, v67
	v_pk_mul_f32 v[210:211], v[190:191], v[86:87]
	v_mul_f32_e32 v67, v194, v67
	v_mul_f32_e32 v191, 0xbfb8aa3b, v201
	v_mul_f32_e32 v194, 0xbfb8aa3b, v209
	v_exp_f32_e32 v191, v191
	v_exp_f32_e32 v194, v194
	v_pk_mul_f32 v[202:203], v[202:203], v[98:99]
	v_pk_mul_f32 v[196:197], v[196:197], v[104:105]
	v_add_f32_e32 v191, 1.0, v191
	v_add_f32_e32 v194, 1.0, v194
	v_rcp_f32_e32 v191, v191
	v_rcp_f32_e32 v194, v194
	v_pk_mul_f32 v[204:205], v[204:205], v[96:97]
	v_pk_mul_f32 v[206:207], v[206:207], v[90:91]
	v_mul_f32_e32 v191, v201, v191
	v_mul_f32_e32 v194, v209, v194
	v_mul_f32_e32 v191, v200, v191
	v_mul_f32_e32 v200, v208, v194
	v_mul_f32_e32 v194, 0xbfb8aa3b, v203
	v_exp_f32_e32 v194, v194
	v_mul_f32_e32 v73, 0xbfb8aa3b, v205
	v_mul_f32_e32 v143, 0xbfb8aa3b, v197
	v_mul_f32_e32 v190, 0xbfb8aa3b, v207
	v_add_f32_e32 v194, 1.0, v194
	v_rcp_f32_e32 v194, v194
	v_exp_f32_e32 v73, v73
	v_exp_f32_e32 v143, v143
	v_exp_f32_e32 v190, v190
	v_mul_f32_e32 v194, v203, v194
	v_mul_f32_e32 v201, v202, v194
; __device__ __forceinline__ unsigned cvt_pk_bf16(float lo, float hi) { unsigned r; asm volatile("v_cvt_pk_bf16_f32 %0, %1, %2" : "=v"(r) : "v"(lo), "v"(hi)); return r; }
; __device__ __forceinline__ float silu_f(float x) { return x * __builtin_amdgcn_rcpf(1.0f + __builtin_amdgcn_exp2f(-1.4426950408889634f * x)); }
;     static __device__ __forceinline__ f32x4 deq(const f32x4 a, const float sa, const f32x4 cm) { if constexpr (!Q) return a; else { const i32x4 i = __builtin_bit_cast(i32x4, a); return (f32x4){(float)i[0] * (sa * cm[0]), (float)i[1] * (sa * cm[1]), (float)i[2] * (sa * cm[2]), (float)i[3] * (sa * cm[ ...
;     __device__ __forceinline__ void operator()(const f32x4 (&acc)[2][2][4][2], const Unit& u, int wr, int wc, int fr, int fq) const {
;     ...
;         for (int ai = 0; ai < 2; ++ai)
; #pragma unroll
;             for (int m = 0; m < 4; ++m) { bf16_t* rowp = (bf16_t*)((unsigned char*)O + (size_t)(row0 + ai * HALF + m * 16) * HROWB) + col0;
;                 float sa = 1.f; if constexpr (Q) sa = SA[row0 + ai * HALF + m * 16];
;                     const f32x4 g0 = deq(acc[ai][0][m][0], sa, cg0), g1 = deq(acc[ai][0][m][1], sa, cg1), u0 = deq(acc[ai][1][m][0], sa, cu0), u1 = deq(acc[ai][1][m][1], sa, cu1);
;                 f32x4 v0, v1;
; #pragma unroll
;                 for (int j = 0; j < 4; ++j) { v0[j] = silu_f(g0[j]) * u0[j]; v1[j] = silu_f(g1[j]) * u1[j]; }
;                 u32x4 w; w.x = cvt_pk_bf16(v0[0], v0[1]); w.y = cvt_pk_bf16(v0[2], v0[3]); w.z = cvt_pk_bf16(v1[0], v1[1]); w.w = cvt_pk_bf16(v1[2], v1[3]);
;                 *(u32x4*)rowp = w; }
	v_mul_f32_e32 v194, 0xbfb8aa3b, v211
	v_exp_f32_e32 v194, v194
	v_add_f32_e32 v73, 1.0, v73
	v_add_f32_e32 v143, 1.0, v143
	v_add_f32_e32 v190, 1.0, v190
	v_add_f32_e32 v194, 1.0, v194
	v_rcp_f32_e32 v73, v73
	v_rcp_f32_e32 v143, v143
	v_rcp_f32_e32 v190, v190
	v_rcp_f32_e32 v194, v194
	v_mul_f32_e32 v73, v205, v73
	v_mul_f32_e32 v143, v197, v143
	v_mul_f32_e32 v190, v207, v190
	v_mul_f32_e32 v194, v211, v194
	v_mul_f32_e32 v73, v204, v73
	v_mul_f32_e32 v143, v196, v143
	v_mul_f32_e32 v190, v206, v190
	v_mul_f32_e32 v202, v210, v194
	v_cvt_pk_bf16_f32 v194, v67, v143
	v_cvt_pk_bf16_f32 v195, v191, v201
	v_cvt_pk_bf16_f32 v196, v73, v190
	v_cvt_pk_bf16_f32 v197, v200, v202
	global_store_dwordx4 v[188:189], v[194:197], off
	v_mov_b32_e32 v190, v224
	v_mad_i64_i32 v[188:189], s[4:5], v155, s86, v[186:187]
	v_lshl_add_u64 v[188:189], v[188:189], 0, v[102:103]
	s_nop 0
	v_pk_mul_f32 v[194:195], v[74:75], v[190:191] op_sel_hi:[1,0]
	s_nop 0
	v_pk_mul_f32 v[194:195], v[194:195], v[84:85]
	v_pk_mul_f32 v[200:201], v[94:95], v[190:191] op_sel_hi:[1,0]
	v_mul_f32_e32 v67, 0xbfb8aa3b, v195
	v_exp_f32_e32 v67, v67
	v_pk_mul_f32 v[208:209], v[182:183], v[190:191] op_sel_hi:[1,0]
	v_pk_mul_f32 v[196:197], v[92:93], v[190:191] op_sel_hi:[1,0]
	v_pk_mul_f32 v[200:201], v[200:201], v[80:81]
	v_add_f32_e32 v67, 1.0, v67
	v_rcp_f32_e32 v67, v67
	v_pk_mul_f32 v[202:203], v[110:111], v[190:191] op_sel_hi:[1,0]
	v_pk_mul_f32 v[204:205], v[178:179], v[190:191] op_sel_hi:[1,0]
	v_pk_mul_f32 v[206:207], v[180:181], v[190:191] op_sel_hi:[1,0]
	v_pk_mul_f32 v[208:209], v[208:209], v[68:69]
	v_pk_mul_f32 v[190:191], v[184:185], v[190:191] op_sel_hi:[1,0]
	v_mul_f32_e32 v67, v195, v67
	v_pk_mul_f32 v[210:211], v[190:191], v[64:65]
	v_mul_f32_e32 v67, v194, v67
	v_mul_f32_e32 v191, 0xbfb8aa3b, v201
	v_mul_f32_e32 v194, 0xbfb8aa3b, v209
	v_exp_f32_e32 v191, v191
	v_exp_f32_e32 v194, v194
	v_pk_mul_f32 v[202:203], v[202:203], v[78:79]
	v_pk_mul_f32 v[196:197], v[196:197], v[82:83]
	v_add_f32_e32 v191, 1.0, v191
	v_add_f32_e32 v194, 1.0, v194
	v_rcp_f32_e32 v191, v191
	v_rcp_f32_e32 v194, v194
	v_pk_mul_f32 v[204:205], v[204:205], v[76:77]
	v_pk_mul_f32 v[206:207], v[206:207], v[70:71]
	v_mul_f32_e32 v191, v201, v191
	v_mul_f32_e32 v194, v209, v194
	v_mul_f32_e32 v191, v200, v191
	v_mul_f32_e32 v200, v208, v194
	v_mul_f32_e32 v194, 0xbfb8aa3b, v203
	v_exp_f32_e32 v194, v194
	v_mul_f32_e32 v73, 0xbfb8aa3b, v205
	v_mul_f32_e32 v143, 0xbfb8aa3b, v197
	v_mul_f32_e32 v190, 0xbfb8aa3b, v207
	v_add_f32_e32 v194, 1.0, v194
	v_rcp_f32_e32 v194, v194
	v_exp_f32_e32 v73, v73
	v_exp_f32_e32 v143, v143
	v_exp_f32_e32 v190, v190
	v_mul_f32_e32 v194, v203, v194
	v_mul_f32_e32 v201, v202, v194
	v_mul_f32_e32 v194, 0xbfb8aa3b, v211
	v_exp_f32_e32 v194, v194
	v_add_f32_e32 v73, 1.0, v73
	v_add_f32_e32 v143, 1.0, v143
	v_add_f32_e32 v190, 1.0, v190
	v_add_f32_e32 v194, 1.0, v194
	v_rcp_f32_e32 v73, v73
	v_rcp_f32_e32 v143, v143
	v_rcp_f32_e32 v190, v190
	v_rcp_f32_e32 v194, v194
	v_mul_f32_e32 v73, v205, v73
	v_mul_f32_e32 v143, v197, v143
	v_mul_f32_e32 v190, v207, v190
	v_mul_f32_e32 v194, v211, v194
	v_mul_f32_e32 v73, v204, v73
	v_mul_f32_e32 v143, v196, v143
	v_mul_f32_e32 v190, v206, v190
	v_mul_f32_e32 v202, v210, v194
	v_cvt_pk_bf16_f32 v194, v67, v143
	v_cvt_pk_bf16_f32 v195, v191, v201
	v_cvt_pk_bf16_f32 v196, v73, v190
	v_cvt_pk_bf16_f32 v197, v200, v202
	global_store_dwordx4 v[188:189], v[194:197], off
	v_mov_b32_e32 v190, v225
	v_add_u32_e32 v67, 0x90, v154
	v_cvt_f32_i32_e32 v195, v52
	v_cvt_f32_i32_e32 v194, v48
	v_mad_i64_i32 v[188:189], s[4:5], v67, s86, v[186:187]
	v_lshl_add_u64 v[188:189], v[188:189], 0, v[102:103]
	s_nop 0
	v_pk_mul_f32 v[196:197], v[74:75], v[190:191] op_sel_hi:[1,0]
	s_nop 0
	v_pk_mul_f32 v[194:195], v[196:197], v[194:195]
	v_cvt_f32_i32_e32 v197, v53
	v_cvt_f32_i32_e32 v196, v49
	v_pk_mul_f32 v[200:201], v[92:93], v[190:191] op_sel_hi:[1,0]
	v_pk_mul_f32 v[202:203], v[94:95], v[190:191] op_sel_hi:[1,0]
	v_mul_f32_e32 v67, 0xbfb8aa3b, v195
	v_pk_mul_f32 v[196:197], v[200:201], v[196:197]
	v_cvt_f32_i32_e32 v201, v54
	v_cvt_f32_i32_e32 v200, v50
	v_pk_mul_f32 v[204:205], v[110:111], v[190:191] op_sel_hi:[1,0]
	v_exp_f32_e32 v67, v67
	v_pk_mul_f32 v[206:207], v[178:179], v[190:191] op_sel_hi:[1,0]
	v_pk_mul_f32 v[200:201], v[202:203], v[200:201]
	v_cvt_f32_i32_e32 v203, v55
	v_cvt_f32_i32_e32 v202, v51
	v_add_f32_e32 v67, 1.0, v67
	v_rcp_f32_e32 v67, v67
	v_pk_mul_f32 v[208:209], v[180:181], v[190:191] op_sel_hi:[1,0]
	v_pk_mul_f32 v[202:203], v[204:205], v[202:203]
	v_cvt_f32_i32_e32 v205, v44
	v_cvt_f32_i32_e32 v204, v40
	v_mul_f32_e32 v67, v195, v67
	v_mul_f32_e32 v67, v194, v67
	v_mul_f32_e32 v143, 0xbfb8aa3b, v197
	v_pk_mul_f32 v[204:205], v[206:207], v[204:205]
	v_cvt_f32_i32_e32 v207, v45
	v_cvt_f32_i32_e32 v206, v41
	v_exp_f32_e32 v143, v143
	v_pk_mul_f32 v[210:211], v[182:183], v[190:191] op_sel_hi:[1,0]
	v_pk_mul_f32 v[190:191], v[184:185], v[190:191] op_sel_hi:[1,0]
	v_pk_mul_f32 v[206:207], v[208:209], v[206:207]
	v_add_f32_e32 v143, 1.0, v143
	v_mul_f32_e32 v194, 0xbfb8aa3b, v207
	v_exp_f32_e32 v194, v194
	v_rcp_f32_e32 v143, v143
	v_cvt_f32_i32_e32 v209, v46
	v_cvt_f32_i32_e32 v208, v42
	v_add_f32_e32 v194, 1.0, v194
	v_rcp_f32_e32 v194, v194
	v_mul_f32_e32 v143, v197, v143
	v_mul_f32_e32 v143, v196, v143
	v_pk_mul_f32 v[208:209], v[210:211], v[208:209]
	v_mul_f32_e32 v194, v207, v194
	v_mul_f32_e32 v196, v206, v194
	v_mul_f32_e32 v194, 0xbfb8aa3b, v201
	v_exp_f32_e32 v194, v194
	v_cvt_f32_i32_e32 v211, v47
	v_cvt_f32_i32_e32 v210, v43
	v_mul_f32_e32 v73, 0xbfb8aa3b, v205
	v_add_f32_e32 v194, 1.0, v194
	v_rcp_f32_e32 v194, v194
; __device__ __forceinline__ unsigned cvt_pk_bf16(float lo, float hi) { unsigned r; asm volatile("v_cvt_pk_bf16_f32 %0, %1, %2" : "=v"(r) : "v"(lo), "v"(hi)); return r; }
; __device__ __forceinline__ float silu_f(float x) { return x * __builtin_amdgcn_rcpf(1.0f + __builtin_amdgcn_exp2f(-1.4426950408889634f * x)); }
;     static __device__ __forceinline__ f32x4 deq(const f32x4 a, const float sa, const f32x4 cm) { if constexpr (!Q) return a; else { const i32x4 i = __builtin_bit_cast(i32x4, a); return (f32x4){(float)i[0] * (sa * cm[0]), (float)i[1] * (sa * cm[1]), (float)i[2] * (sa * cm[2]), (float)i[3] * (sa * cm[ ...
;     __device__ __forceinline__ void operator()(const f32x4 (&acc)[2][2][4][2], const Unit& u, int wr, int wc, int fr, int fq) const {
;     ...
;         for (int ai = 0; ai < 2; ++ai)
; #pragma unroll
;             for (int m = 0; m < 4; ++m) { bf16_t* rowp = (bf16_t*)((unsigned char*)O + (size_t)(row0 + ai * HALF + m * 16) * HROWB) + col0;
;                 float sa = 1.f; if constexpr (Q) sa = SA[row0 + ai * HALF + m * 16];
;                     const f32x4 g0 = deq(acc[ai][0][m][0], sa, cg0), g1 = deq(acc[ai][0][m][1], sa, cg1), u0 = deq(acc[ai][1][m][0], sa, cu0), u1 = deq(acc[ai][1][m][1], sa, cu1);
;                 f32x4 v0, v1;
; #pragma unroll
;                 for (int j = 0; j < 4; ++j) { v0[j] = silu_f(g0[j]) * u0[j]; v1[j] = silu_f(g1[j]) * u1[j]; }
;                 u32x4 w; w.x = cvt_pk_bf16(v0[0], v0[1]); w.y = cvt_pk_bf16(v0[2], v0[3]); w.z = cvt_pk_bf16(v1[0], v1[1]); w.w = cvt_pk_bf16(v1[2], v1[3]);
;                 *(u32x4*)rowp = w; }
	v_pk_mul_f32 v[190:191], v[190:191], v[210:211]
	v_exp_f32_e32 v73, v73
	v_mul_f32_e32 v194, v201, v194
	v_mul_f32_e32 v195, v200, v194
	v_mul_f32_e32 v194, 0xbfb8aa3b, v209
	v_exp_f32_e32 v194, v194
	v_add_f32_e32 v73, 1.0, v73
	v_rcp_f32_e32 v73, v73
	v_add_f32_e32 v194, 1.0, v194
	v_rcp_f32_e32 v194, v194
	v_mul_f32_e32 v73, v205, v73
	v_mul_f32_e32 v73, v204, v73
	v_mul_f32_e32 v194, v209, v194
	v_mul_f32_e32 v197, v208, v194
	v_mul_f32_e32 v194, 0xbfb8aa3b, v203
	v_exp_f32_e32 v194, v194
	s_nop 0
	v_add_f32_e32 v194, 1.0, v194
	v_rcp_f32_e32 v194, v194
	s_nop 0
	v_mul_f32_e32 v194, v203, v194
	v_mul_f32_e32 v200, v202, v194
	v_mul_f32_e32 v194, 0xbfb8aa3b, v191
	v_exp_f32_e32 v194, v194
	s_nop 0
	v_add_f32_e32 v194, 1.0, v194
	v_rcp_f32_e32 v194, v194
	s_nop 0
	v_mul_f32_e32 v191, v191, v194
	v_mul_f32_e32 v190, v190, v191
	v_cvt_pk_bf16_f32 v194, v67, v143
	v_cvt_pk_bf16_f32 v195, v195, v200
	v_cvt_pk_bf16_f32 v196, v73, v196
	v_cvt_pk_bf16_f32 v197, v197, v190
	global_store_dwordx4 v[188:189], v[194:197], off
	v_mov_b32_e32 v190, v226
	v_add_u32_e32 v67, 0xa0, v154
	v_cvt_f32_i32_e32 v195, v36
	v_cvt_f32_i32_e32 v194, v28
	v_mad_i64_i32 v[188:189], s[4:5], v67, s86, v[186:187]
	v_lshl_add_u64 v[188:189], v[188:189], 0, v[102:103]
	s_nop 0
	v_pk_mul_f32 v[196:197], v[74:75], v[190:191] op_sel_hi:[1,0]
	s_nop 0
	v_pk_mul_f32 v[194:195], v[196:197], v[194:195]
	v_cvt_f32_i32_e32 v197, v37
	v_cvt_f32_i32_e32 v196, v29
	v_pk_mul_f32 v[200:201], v[92:93], v[190:191] op_sel_hi:[1,0]
	v_pk_mul_f32 v[202:203], v[94:95], v[190:191] op_sel_hi:[1,0]
	v_mul_f32_e32 v67, 0xbfb8aa3b, v195
	v_pk_mul_f32 v[196:197], v[200:201], v[196:197]
	v_cvt_f32_i32_e32 v201, v38
	v_cvt_f32_i32_e32 v200, v30
	v_pk_mul_f32 v[204:205], v[110:111], v[190:191] op_sel_hi:[1,0]
	v_exp_f32_e32 v67, v67
	v_pk_mul_f32 v[206:207], v[178:179], v[190:191] op_sel_hi:[1,0]
	v_pk_mul_f32 v[200:201], v[202:203], v[200:201]
	v_cvt_f32_i32_e32 v203, v39
	v_cvt_f32_i32_e32 v202, v31
	v_add_f32_e32 v67, 1.0, v67
	v_rcp_f32_e32 v67, v67
	v_pk_mul_f32 v[208:209], v[180:181], v[190:191] op_sel_hi:[1,0]
	v_pk_mul_f32 v[202:203], v[204:205], v[202:203]
	v_cvt_f32_i32_e32 v205, v24
	v_cvt_f32_i32_e32 v204, v16
	v_mul_f32_e32 v67, v195, v67
	v_mul_f32_e32 v67, v194, v67
	v_mul_f32_e32 v143, 0xbfb8aa3b, v197
	v_pk_mul_f32 v[204:205], v[206:207], v[204:205]
	v_cvt_f32_i32_e32 v207, v25
	v_cvt_f32_i32_e32 v206, v17
	v_exp_f32_e32 v143, v143
	v_pk_mul_f32 v[210:211], v[182:183], v[190:191] op_sel_hi:[1,0]
	v_pk_mul_f32 v[190:191], v[184:185], v[190:191] op_sel_hi:[1,0]
	v_pk_mul_f32 v[206:207], v[208:209], v[206:207]
	v_add_f32_e32 v143, 1.0, v143
	v_mul_f32_e32 v194, 0xbfb8aa3b, v207
	v_exp_f32_e32 v194, v194
	v_rcp_f32_e32 v143, v143
	v_cvt_f32_i32_e32 v209, v26
	v_cvt_f32_i32_e32 v208, v18
	v_add_f32_e32 v194, 1.0, v194
	v_rcp_f32_e32 v194, v194
	v_mul_f32_e32 v143, v197, v143
	v_mul_f32_e32 v143, v196, v143
	v_pk_mul_f32 v[208:209], v[210:211], v[208:209]
	v_mul_f32_e32 v194, v207, v194
	v_mul_f32_e32 v196, v206, v194
	v_mul_f32_e32 v194, 0xbfb8aa3b, v201
	v_exp_f32_e32 v194, v194
	v_cvt_f32_i32_e32 v211, v27
	v_cvt_f32_i32_e32 v210, v19
	v_mul_f32_e32 v73, 0xbfb8aa3b, v205
	v_add_f32_e32 v194, 1.0, v194
	v_rcp_f32_e32 v194, v194
	v_pk_mul_f32 v[190:191], v[190:191], v[210:211]
	v_exp_f32_e32 v73, v73
	v_mul_f32_e32 v194, v201, v194
	v_mul_f32_e32 v195, v200, v194
	v_mul_f32_e32 v194, 0xbfb8aa3b, v209
	v_exp_f32_e32 v194, v194
	v_add_f32_e32 v73, 1.0, v73
	v_rcp_f32_e32 v73, v73
	v_add_f32_e32 v194, 1.0, v194
	v_rcp_f32_e32 v194, v194
	v_mul_f32_e32 v73, v205, v73
	v_mul_f32_e32 v73, v204, v73
	v_mul_f32_e32 v194, v209, v194
	v_mul_f32_e32 v197, v208, v194
	v_mul_f32_e32 v194, 0xbfb8aa3b, v203
	v_exp_f32_e32 v194, v194
	s_nop 0
	v_add_f32_e32 v194, 1.0, v194
	v_rcp_f32_e32 v194, v194
	s_nop 0
	v_mul_f32_e32 v194, v203, v194
	v_mul_f32_e32 v200, v202, v194
	v_mul_f32_e32 v194, 0xbfb8aa3b, v191
	v_exp_f32_e32 v194, v194
	s_nop 0
	v_add_f32_e32 v194, 1.0, v194
	v_rcp_f32_e32 v194, v194
	s_nop 0
	v_mul_f32_e32 v191, v191, v194
	v_mul_f32_e32 v190, v190, v191
	v_cvt_pk_bf16_f32 v194, v67, v143
	v_cvt_pk_bf16_f32 v195, v195, v200
	v_cvt_pk_bf16_f32 v196, v73, v196
	v_cvt_pk_bf16_f32 v197, v197, v190
	global_store_dwordx4 v[188:189], v[194:197], off
	v_mov_b32_e32 v188, v227
	v_cvt_f32_i32_e32 v191, v12
	v_cvt_f32_i32_e32 v190, v8
	v_add_u32_e32 v67, 0xb0, v154
	v_mad_i64_i32 v[186:187], s[4:5], v67, s86, v[186:187]
	s_nop 0
	v_pk_mul_f32 v[74:75], v[74:75], v[188:189] op_sel_hi:[1,0]
	s_nop 0
	v_pk_mul_f32 v[74:75], v[74:75], v[190:191]
	v_cvt_f32_i32_e32 v191, v13
	v_mul_f32_e32 v67, 0xbfb8aa3b, v75
	v_cvt_f32_i32_e32 v190, v9
	v_exp_f32_e32 v67, v67
	v_pk_mul_f32 v[92:93], v[92:93], v[188:189] op_sel_hi:[1,0]
	v_pk_mul_f32 v[94:95], v[94:95], v[188:189] op_sel_hi:[1,0]
	v_pk_mul_f32 v[92:93], v[92:93], v[190:191]
	v_cvt_f32_i32_e32 v191, v14
	v_cvt_f32_i32_e32 v190, v10
	v_add_f32_e32 v67, 1.0, v67
	v_rcp_f32_e32 v67, v67
	v_pk_mul_f32 v[110:111], v[110:111], v[188:189] op_sel_hi:[1,0]
	v_pk_mul_f32 v[94:95], v[94:95], v[190:191]
	v_cvt_f32_i32_e32 v191, v15
	v_cvt_f32_i32_e32 v190, v11
	v_mul_f32_e32 v67, v75, v67
	v_mul_f32_e32 v67, v74, v67
	v_mul_f32_e32 v74, 0xbfb8aa3b, v93
	v_exp_f32_e32 v74, v74
	v_pk_mul_f32 v[110:111], v[110:111], v[190:191]
	v_cvt_f32_i32_e32 v191, v4
	v_cvt_f32_i32_e32 v190, v0
	v_pk_mul_f32 v[178:179], v[178:179], v[188:189] op_sel_hi:[1,0]
	v_add_f32_e32 v74, 1.0, v74
	v_rcp_f32_e32 v74, v74
	v_pk_mul_f32 v[178:179], v[178:179], v[190:191]
	v_cvt_f32_i32_e32 v191, v5
	v_cvt_f32_i32_e32 v190, v1
	v_pk_mul_f32 v[180:181], v[180:181], v[188:189] op_sel_hi:[1,0]
; __device__ __forceinline__ unsigned cvt_pk_bf16(float lo, float hi) { unsigned r; asm volatile("v_cvt_pk_bf16_f32 %0, %1, %2" : "=v"(r) : "v"(lo), "v"(hi)); return r; }
; __device__ __forceinline__ float silu_f(float x) { return x * __builtin_amdgcn_rcpf(1.0f + __builtin_amdgcn_exp2f(-1.4426950408889634f * x)); }
;     __device__ __forceinline__ void operator()(const f32x4 (&acc)[2][2][4][2], const Unit& u, int wr, int wc, int fr, int fq) const {
;     ...
;         if (u.pn * HALF >= H16) {
; #pragma unroll
;             for (int ai = 0; ai < 2; ++ai)
; #pragma unroll
;                 for (int m = 0; m < 4; ++m) { unsigned char* rowp = (unsigned char*)O + (size_t)(row0 + ai * HALF + m * 16) * HROWB + H16 * 2 + (col0 - H16);
;                     float sa = 1.f; if constexpr (Q) sa = SA[row0 + ai * HALF + m * 16];
;                     const f32x4 g0 = deq(acc[ai][0][m][0], sa, cg0), g1 = deq(acc[ai][0][m][1], sa, cg1), u0 = deq(acc[ai][1][m][0], sa, cu0), u1 = deq(acc[ai][1][m][1], sa, cu1);
;                     float v[8];
; #pragma unroll
;                     for (int j = 0; j < 4; ++j) { v[j] = __builtin_amdgcn_fmed3f(silu_f(g0[j]) * u0[j] * 4.0f, -448.f, 448.f); v[4 + j] = __builtin_amdgcn_fmed3f(silu_f(g1[j]) * u1[j] * 4.0f, -448.f, 448.f); }
;                     int w0 = __builtin_amdgcn_cvt_pk_fp8_f32(v[0], v[1], 0, false); w0 = __builtin_amdgcn_cvt_pk_fp8_f32(v[2], v[3], w0, true);
;                     int w1 = __builtin_amdgcn_cvt_pk_fp8_f32(v[4], v[5], 0, false); w1 = __builtin_amdgcn_cvt_pk_fp8_f32(v[6], v[7], w1, true);
;     ...
;         for (int ai = 0; ai < 2; ++ai)
; #pragma unroll
;             for (int m = 0; m < 4; ++m) { bf16_t* rowp = (bf16_t*)((unsigned char*)O + (size_t)(row0 + ai * HALF + m * 16) * HROWB) + col0;
;                 float sa = 1.f; if constexpr (Q) sa = SA[row0 + ai * HALF + m * 16];
;                     const f32x4 g0 = deq(acc[ai][0][m][0], sa, cg0), g1 = deq(acc[ai][0][m][1], sa, cg1), u0 = deq(acc[ai][1][m][0], sa, cu0), u1 = deq(acc[ai][1][m][1], sa, cu1);
;                 f32x4 v0, v1;
; #pragma unroll
;                 for (int j = 0; j < 4; ++j) { v0[j] = silu_f(g0[j]) * u0[j]; v1[j] = silu_f(g1[j]) * u1[j]; }
;                 u32x4 w; w.x = cvt_pk_bf16(v0[0], v0[1]); w.y = cvt_pk_bf16(v0[2], v0[3]); w.z = cvt_pk_bf16(v1[0], v1[1]); w.w = cvt_pk_bf16(v1[2], v1[3]);
;                 *(u32x4*)rowp = w; }
	v_mul_f32_e32 v74, v93, v74
	v_mul_f32_e32 v92, v92, v74
	v_pk_mul_f32 v[180:181], v[180:181], v[190:191]
	v_cvt_f32_i32_e32 v191, v6
	v_mul_f32_e32 v74, 0xbfb8aa3b, v181
	v_exp_f32_e32 v74, v74
	v_cvt_f32_i32_e32 v190, v2
	v_pk_mul_f32 v[182:183], v[182:183], v[188:189] op_sel_hi:[1,0]
	v_pk_mul_f32 v[184:185], v[184:185], v[188:189] op_sel_hi:[1,0]
	v_add_f32_e32 v74, 1.0, v74
	v_rcp_f32_e32 v74, v74
	v_pk_mul_f32 v[182:183], v[182:183], v[190:191]
	v_cvt_f32_i32_e32 v191, v7
	v_cvt_f32_i32_e32 v190, v3
	v_mul_f32_e32 v74, v181, v74
	v_mul_f32_e32 v143, v180, v74
	v_mul_f32_e32 v74, 0xbfb8aa3b, v95
	v_exp_f32_e32 v74, v74
	v_pk_mul_f32 v[184:185], v[184:185], v[190:191]
	v_mul_f32_e32 v73, 0xbfb8aa3b, v179
	v_exp_f32_e32 v73, v73
	v_add_f32_e32 v74, 1.0, v74
	v_rcp_f32_e32 v74, v74
	v_cvt_pk_bf16_f32 v92, v67, v92
	v_add_f32_e32 v73, 1.0, v73
	v_rcp_f32_e32 v73, v73
	v_mul_f32_e32 v74, v95, v74
	v_mul_f32_e32 v93, v94, v74
	v_mul_f32_e32 v74, 0xbfb8aa3b, v183
	v_exp_f32_e32 v74, v74
	v_mul_f32_e32 v73, v179, v73
	v_mul_f32_e32 v73, v178, v73
	v_add_f32_e32 v74, 1.0, v74
	v_rcp_f32_e32 v74, v74
	s_nop 0
	v_mul_f32_e32 v74, v183, v74
	v_mul_f32_e32 v95, v182, v74
	v_mul_f32_e32 v74, 0xbfb8aa3b, v111
	v_exp_f32_e32 v74, v74
	s_nop 0
	v_add_f32_e32 v74, 1.0, v74
	v_rcp_f32_e32 v74, v74
	s_nop 0
	v_mul_f32_e32 v74, v111, v74
	v_mul_f32_e32 v94, v110, v74
	v_mul_f32_e32 v74, 0xbfb8aa3b, v185
	v_exp_f32_e32 v74, v74
	v_cvt_pk_bf16_f32 v93, v93, v94
	v_cvt_pk_bf16_f32 v94, v73, v143
	s_nop 0
	v_add_f32_e32 v74, 1.0, v74
	v_rcp_f32_e32 v74, v74
	s_nop 0
	v_mul_f32_e32 v74, v185, v74
	v_mul_f32_e32 v110, v184, v74
	v_lshl_add_u64 v[74:75], v[186:187], 0, v[102:103]
	v_cvt_pk_bf16_f32 v95, v95, v110
	global_store_dwordx4 v[74:75], v[92:95], off
	s_cbranch_execnz .LBB0_557
.LBB0_559:
	global_load_dword v220, v[158:159], off
	global_load_dword v221, v[158:159], off offset:64
	global_load_dword v222, v[158:159], off offset:128
	global_load_dword v223, v[158:159], off offset:192
	global_load_dword v224, v[158:159], off offset:512
	global_load_dword v225, v[158:159], off offset:576
	global_load_dword v226, v[158:159], off offset:640
	global_load_dword v227, v[158:159], off offset:704
	s_waitcnt vmcnt(0)
	v_mov_b32_e32 v94, v220
	v_mov_b32_e32 v75, v32
	v_mov_b32_e32 v32, v61
	v_mov_b32_e32 v74, v60
	v_lshl_add_u64 v[92:93], v[176:177], 0, v[156:157]
	v_ashrrev_i32_e32 v143, 31, v142
	v_cvt_f32_i32_e32 v53, v53
	v_cvt_f32_i32_e32 v55, v55
	v_cvt_f32_i32_e32 v45, v45
	v_cvt_f32_i32_e32 v47, v47
	v_cvt_f32_i32_e32 v37, v37
	v_cvt_f32_i32_e32 v39, v39
	v_cvt_f32_i32_e32 v25, v25
	v_cvt_f32_i32_e32 v27, v27
	v_cvt_f32_i32_e32 v13, v13
	v_cvt_f32_i32_e32 v15, v15
	v_cvt_f32_i32_e32 v5, v5
	v_cvt_f32_i32_e32 v7, v7
	v_pk_mul_f32 v[60:61], v[32:33], v[94:95] op_sel_hi:[1,0]
	s_nop 0
	v_pk_mul_f32 v[110:111], v[60:61], v[172:173]
	v_mov_b32_e32 v61, v34
	v_mov_b32_e32 v34, v63
	v_mov_b32_e32 v60, v62
	v_pk_mul_f32 v[62:63], v[34:35], v[94:95] op_sel_hi:[1,0]
	v_pk_mul_f32 v[102:103], v[74:75], v[94:95] op_sel_hi:[1,0]
	v_pk_mul_f32 v[168:169], v[62:63], v[168:169]
	v_mov_b32_e32 v63, v20
	v_mov_b32_e32 v20, v57
	v_pk_mul_f32 v[172:173], v[60:61], v[94:95] op_sel_hi:[1,0]
	v_mov_b32_e32 v62, v56
	v_pk_mul_f32 v[56:57], v[20:21], v[94:95] op_sel_hi:[1,0]
	v_pk_mul_f32 v[102:103], v[102:103], v[174:175]
	v_pk_mul_f32 v[170:171], v[172:173], v[170:171]
	v_pk_mul_f32 v[172:173], v[62:63], v[94:95] op_sel_hi:[1,0]
	v_pk_mul_f32 v[164:165], v[56:57], v[164:165]
	v_mov_b32_e32 v56, v58
	v_mov_b32_e32 v57, v22
	v_mov_b32_e32 v22, v59
	v_pk_mul_f32 v[166:167], v[172:173], v[166:167]
	v_pk_mul_f32 v[172:173], v[56:57], v[94:95] op_sel_hi:[1,0]
	v_pk_mul_f32 v[58:59], v[22:23], v[94:95] op_sel_hi:[1,0]
	v_mul_f32_e32 v67, 0xbfb8aa3b, v103
	v_mul_f32_e32 v73, 0xbfb8aa3b, v111
	v_mul_f32_e32 v95, 0xbfb8aa3b, v169
	v_exp_f32_e32 v67, v67
	v_exp_f32_e32 v73, v73
	v_exp_f32_e32 v95, v95
	v_mul_f32_e32 v94, 0xbfb8aa3b, v171
	v_add_f32_e32 v67, 1.0, v67
	v_add_f32_e32 v73, 1.0, v73
	v_exp_f32_e32 v94, v94
	v_add_f32_e32 v95, 1.0, v95
	v_rcp_f32_e32 v67, v67
	v_rcp_f32_e32 v73, v73
	v_rcp_f32_e32 v95, v95
	v_add_f32_e32 v94, 1.0, v94
	v_mul_f32_e32 v67, v103, v67
	v_mul_f32_e32 v73, v111, v73
	v_rcp_f32_e32 v94, v94
	v_mul_f32_e32 v95, v169, v95
	v_mul_f32_e32 v67, v102, v67
	v_mul_f32_e32 v73, v110, v73
	v_mul_f32_e32 v95, v168, v95
	v_pk_mul_f32 v[58:59], v[58:59], v[160:161]
	v_mul_f32_e32 v67, 4.0, v67
	v_mov_b32_e32 v160, 0x43e00000
	v_mul_f32_e32 v73, 4.0, v73
	v_mul_f32_e32 v95, 4.0, v95
	v_med3_f32 v102, v67, s87, v160
	v_mul_f32_e32 v67, 0xbfb8aa3b, v167
	v_med3_f32 v103, v73, s87, v160
	v_mul_f32_e32 v73, 0xbfb8aa3b, v165
	v_med3_f32 v111, v95, s87, v160
	v_mul_f32_e32 v95, 0xbfb8aa3b, v59
	v_exp_f32_e32 v67, v67
	v_exp_f32_e32 v73, v73
	v_mul_f32_e32 v94, v171, v94
	v_exp_f32_e32 v95, v95
	v_mul_f32_e32 v94, v170, v94
	v_pk_mul_f32 v[162:163], v[172:173], v[162:163]
	v_mul_f32_e32 v94, 4.0, v94
	v_med3_f32 v110, v94, s87, v160
	v_mul_f32_e32 v94, 0xbfb8aa3b, v163
	v_add_f32_e32 v67, 1.0, v67
	v_add_f32_e32 v73, 1.0, v73
	v_exp_f32_e32 v94, v94
	v_add_f32_e32 v95, 1.0, v95
	v_rcp_f32_e32 v67, v67
	v_rcp_f32_e32 v73, v73
	v_rcp_f32_e32 v95, v95
	v_add_f32_e32 v94, 1.0, v94
	v_mul_f32_e32 v67, v167, v67
	v_mul_f32_e32 v73, v165, v73
	v_rcp_f32_e32 v94, v94
	v_mul_f32_e32 v59, v59, v95
	v_mul_f32_e32 v67, v166, v67
	v_mul_f32_e32 v73, v164, v73
	v_mul_f32_e32 v58, v58, v59
	v_mul_f32_e32 v67, 4.0, v67
	v_mul_f32_e32 v73, 4.0, v73
	v_mul_f32_e32 v58, 4.0, v58
	v_med3_f32 v67, v67, s87, v160
	v_med3_f32 v73, v73, s87, v160
	v_med3_f32 v95, v58, s87, v160
	v_mov_b32_e32 v58, v193
; __device__ __forceinline__ float silu_f(float x) { return x * __builtin_amdgcn_rcpf(1.0f + __builtin_amdgcn_exp2f(-1.4426950408889634f * x)); }
;     static __device__ __forceinline__ f32x4 deq(const f32x4 a, const float sa, const f32x4 cm) { if constexpr (!Q) return a; else { const i32x4 i = __builtin_bit_cast(i32x4, a); return (f32x4){(float)i[0] * (sa * cm[0]), (float)i[1] * (sa * cm[1]), (float)i[2] * (sa * cm[2]), (float)i[3] * (sa * cm[3])}; } }
;     __device__ __forceinline__ void operator()(const f32x4 (&acc)[2][2][4][2], const Unit& u, int wr, int wc, int fr, int fq) const {
;     ...
;         if (u.pn * HALF >= H16) {
; #pragma unroll
;             for (int ai = 0; ai < 2; ++ai)
; #pragma unroll
;                 for (int m = 0; m < 4; ++m) { unsigned char* rowp = (unsigned char*)O + (size_t)(row0 + ai * HALF + m * 16) * HROWB + H16 * 2 + (col0 - H16);
;                     float sa = 1.f; if constexpr (Q) sa = SA[row0 + ai * HALF + m * 16];
;                     const f32x4 g0 = deq(acc[ai][0][m][0], sa, cg0), g1 = deq(acc[ai][0][m][1], sa, cg1), u0 = deq(acc[ai][1][m][0], sa, cu0), u1 = deq(acc[ai][1][m][1], sa, cu1);
;                     float v[8];
; #pragma unroll
;                     for (int j = 0; j < 4; ++j) { v[j] = __builtin_amdgcn_fmed3f(silu_f(g0[j]) * u0[j] * 4.0f, -448.f, 448.f); v[4 + j] = __builtin_amdgcn_fmed3f(silu_f(g1[j]) * u1[j] * 4.0f, -448.f, 448.f); }
;                     int w0 = __builtin_amdgcn_cvt_pk_fp8_f32(v[0], v[1], 0, false); w0 = __builtin_amdgcn_cvt_pk_fp8_f32(v[2], v[3], w0, true);
;                     int w1 = __builtin_amdgcn_cvt_pk_fp8_f32(v[4], v[5], 0, false); w1 = __builtin_amdgcn_cvt_pk_fp8_f32(v[6], v[7], w1, true);
;                     typedef int i32x2 __attribute__((ext_vector_type(2)));
;                     *(i32x2*)rowp = (i32x2){w0, w1}; }
	v_mov_b32_e32 v59, v193
	v_mul_f32_e32 v94, v163, v94
	v_cvt_pk_fp8_f32 v58, v102, v103
	v_cvt_pk_fp8_f32 v59, v67, v73
	v_mul_f32_e32 v94, v162, v94
	v_mul_f32_e32 v94, 4.0, v94
	v_med3_f32 v94, v94, s87, v160
	v_cvt_pk_fp8_f32 v58, v110, v111 op_sel:[0,0,1]
	v_cvt_pk_fp8_f32 v59, v94, v95 op_sel:[0,0,1]
	v_lshl_add_u64 v[94:95], v[142:143], 2, s[92:93]
	global_store_dwordx2 v[92:93], v[58:59], off offset:1536
	v_mov_b32_e32 v94, v221
	v_mov_b64_e32 v[58:59], s[82:83]
	v_mad_i64_i32 v[92:93], s[4:5], v142, s86, v[58:59]
	v_lshl_add_u64 v[92:93], v[92:93], 0, v[156:157]
	s_nop 0
	v_pk_mul_f32 v[102:103], v[74:75], v[94:95] op_sel_hi:[1,0]
	s_nop 0
	v_pk_mul_f32 v[102:103], v[102:103], v[140:141]
	v_pk_mul_f32 v[110:111], v[32:33], v[94:95] op_sel_hi:[1,0]
	v_mul_f32_e32 v67, 0xbfb8aa3b, v103
	v_exp_f32_e32 v67, v67
	v_pk_mul_f32 v[110:111], v[110:111], v[138:139]
	v_pk_mul_f32 v[138:139], v[60:61], v[94:95] op_sel_hi:[1,0]
	v_add_f32_e32 v67, 1.0, v67
	v_rcp_f32_e32 v67, v67
	v_pk_mul_f32 v[136:137], v[138:139], v[136:137]
	v_pk_mul_f32 v[138:139], v[34:35], v[94:95] op_sel_hi:[1,0]
	v_mul_f32_e32 v67, v103, v67
	v_mul_f32_e32 v67, v102, v67
	v_mul_f32_e32 v102, 0xbfb8aa3b, v111
	v_exp_f32_e32 v102, v102
	v_pk_mul_f32 v[134:135], v[138:139], v[134:135]
	v_pk_mul_f32 v[138:139], v[62:63], v[94:95] op_sel_hi:[1,0]
	v_mul_f32_e32 v67, 4.0, v67
	v_pk_mul_f32 v[132:133], v[138:139], v[132:133]
	v_pk_mul_f32 v[138:139], v[20:21], v[94:95] op_sel_hi:[1,0]
	v_add_f32_e32 v102, 1.0, v102
	v_pk_mul_f32 v[130:131], v[138:139], v[130:131]
	v_pk_mul_f32 v[138:139], v[56:57], v[94:95] op_sel_hi:[1,0]
	v_pk_mul_f32 v[94:95], v[22:23], v[94:95] op_sel_hi:[1,0]
	v_rcp_f32_e32 v102, v102
	v_pk_mul_f32 v[94:95], v[94:95], v[126:127]
	v_mul_f32_e32 v73, 0xbfb8aa3b, v133
	v_mul_f32_e32 v103, 0xbfb8aa3b, v131
	v_mul_f32_e32 v127, 0xbfb8aa3b, v95
	v_exp_f32_e32 v73, v73
	v_exp_f32_e32 v103, v103
	v_exp_f32_e32 v127, v127
	v_pk_mul_f32 v[128:129], v[138:139], v[128:129]
	v_mul_f32_e32 v102, v111, v102
	v_mul_f32_e32 v102, v110, v102
	v_mul_f32_e32 v110, 0xbfb8aa3b, v137
	v_mul_f32_e32 v111, 0xbfb8aa3b, v129
	v_mul_f32_e32 v126, 0xbfb8aa3b, v135
	v_add_f32_e32 v73, 1.0, v73
	v_add_f32_e32 v103, 1.0, v103
	v_exp_f32_e32 v110, v110
	v_exp_f32_e32 v111, v111
	v_exp_f32_e32 v126, v126
	v_add_f32_e32 v127, 1.0, v127
	v_rcp_f32_e32 v73, v73
	v_rcp_f32_e32 v103, v103
	v_rcp_f32_e32 v127, v127
	v_add_f32_e32 v110, 1.0, v110
	v_add_f32_e32 v111, 1.0, v111
	v_add_f32_e32 v126, 1.0, v126
	v_mul_f32_e32 v73, v133, v73
	v_mul_f32_e32 v103, v131, v103
	v_rcp_f32_e32 v110, v110
	v_rcp_f32_e32 v111, v111
	v_rcp_f32_e32 v126, v126
	v_mul_f32_e32 v95, v95, v127
	v_mul_f32_e32 v73, v132, v73
	v_mul_f32_e32 v103, v130, v103
	v_mul_f32_e32 v94, v94, v95
	v_mul_f32_e32 v73, 4.0, v73
	v_mul_f32_e32 v102, 4.0, v102
	v_mul_f32_e32 v103, 4.0, v103
	v_mul_f32_e32 v94, 4.0, v94
	v_med3_f32 v67, v67, s87, v160
	v_med3_f32 v73, v73, s87, v160
	v_med3_f32 v102, v102, s87, v160
	v_med3_f32 v103, v103, s87, v160
	v_med3_f32 v127, v94, s87, v160
	v_mov_b32_e32 v94, v193
	v_mov_b32_e32 v95, v193
	v_mul_f32_e32 v110, v137, v110
	v_mul_f32_e32 v111, v129, v111
	v_mul_f32_e32 v126, v135, v126
	v_cvt_pk_fp8_f32 v94, v67, v102
	v_cvt_pk_fp8_f32 v95, v73, v103
	v_mul_f32_e32 v110, v136, v110
	v_mul_f32_e32 v111, v128, v111
	v_mul_f32_e32 v126, v134, v126
	v_mul_f32_e32 v110, 4.0, v110
	v_mul_f32_e32 v111, 4.0, v111
	v_mul_f32_e32 v126, 4.0, v126
	v_med3_f32 v110, v110, s87, v160
	v_med3_f32 v111, v111, s87, v160
	v_med3_f32 v126, v126, s87, v160
	v_cvt_pk_fp8_f32 v94, v110, v126 op_sel:[0,0,1]
	v_cvt_pk_fp8_f32 v95, v111, v127 op_sel:[0,0,1]
	v_ashrrev_i32_e32 v73, 31, v72
	global_store_dwordx2 v[92:93], v[94:95], off offset:1536
	v_mad_i64_i32 v[92:93], s[4:5], v72, s86, v[58:59]
	v_lshl_add_u64 v[72:73], v[72:73], 2, s[92:93]
	v_mov_b32_e32 v72, v222
	v_lshl_add_u64 v[92:93], v[92:93], 0, v[156:157]
	s_nop 0
	v_pk_mul_f32 v[94:95], v[74:75], v[72:73] op_sel_hi:[1,0]
	s_nop 0
	v_pk_mul_f32 v[94:95], v[94:95], v[124:125]
	v_pk_mul_f32 v[102:103], v[32:33], v[72:73] op_sel_hi:[1,0]
	v_mul_f32_e32 v67, 0xbfb8aa3b, v95
	v_exp_f32_e32 v67, v67
	v_pk_mul_f32 v[102:103], v[102:103], v[122:123]
	v_pk_mul_f32 v[110:111], v[60:61], v[72:73] op_sel_hi:[1,0]
	v_add_f32_e32 v67, 1.0, v67
	v_rcp_f32_e32 v67, v67
	v_pk_mul_f32 v[110:111], v[110:111], v[120:121]
	v_pk_mul_f32 v[120:121], v[34:35], v[72:73] op_sel_hi:[1,0]
	v_mul_f32_e32 v67, v95, v67
	v_mul_f32_e32 v95, 0xbfb8aa3b, v103
	v_exp_f32_e32 v95, v95
	v_pk_mul_f32 v[118:119], v[120:121], v[118:119]
	v_pk_mul_f32 v[120:121], v[62:63], v[72:73] op_sel_hi:[1,0]
	v_mul_f32_e32 v67, v94, v67
	v_add_f32_e32 v95, 1.0, v95
	v_rcp_f32_e32 v95, v95
	v_pk_mul_f32 v[116:117], v[120:121], v[116:117]
	v_pk_mul_f32 v[120:121], v[20:21], v[72:73] op_sel_hi:[1,0]
	v_mul_f32_e32 v94, 0xbfb8aa3b, v117
	v_mul_f32_e32 v95, v103, v95
	v_mul_f32_e32 v103, 0xbfb8aa3b, v111
	v_exp_f32_e32 v103, v103
	v_pk_mul_f32 v[114:115], v[120:121], v[114:115]
	v_pk_mul_f32 v[120:121], v[56:57], v[72:73] op_sel_hi:[1,0]
	v_pk_mul_f32 v[72:73], v[22:23], v[72:73] op_sel_hi:[1,0]
	v_add_f32_e32 v103, 1.0, v103
	v_rcp_f32_e32 v103, v103
	v_pk_mul_f32 v[72:73], v[72:73], v[108:109]
	v_mul_f32_e32 v95, v102, v95
	v_mul_f32_e32 v102, 0xbfb8aa3b, v115
	v_mul_f32_e32 v103, v111, v103
	v_mul_f32_e32 v103, v110, v103
	v_mul_f32_e32 v110, 0xbfb8aa3b, v73
	v_exp_f32_e32 v94, v94
	v_exp_f32_e32 v102, v102
	v_exp_f32_e32 v110, v110
	v_pk_mul_f32 v[112:113], v[120:121], v[112:113]
	v_mul_f32_e32 v109, 0xbfb8aa3b, v119
	v_mul_f32_e32 v108, 0xbfb8aa3b, v113
	v_add_f32_e32 v94, 1.0, v94
	v_add_f32_e32 v102, 1.0, v102
; __device__ __forceinline__ float silu_f(float x) { return x * __builtin_amdgcn_rcpf(1.0f + __builtin_amdgcn_exp2f(-1.4426950408889634f * x)); }
;     static __device__ __forceinline__ f32x4 deq(const f32x4 a, const float sa, const f32x4 cm) { if constexpr (!Q) return a; else { const i32x4 i = __builtin_bit_cast(i32x4, a); return (f32x4){(float)i[0] * (sa * cm[0]), (float)i[1] * (sa * cm[1]), (float)i[2] * (sa * cm[2]), (float)i[3] * (sa * cm[3])}; } }
;     __device__ __forceinline__ void operator()(const f32x4 (&acc)[2][2][4][2], const Unit& u, int wr, int wc, int fr, int fq) const {
;     ...
;         if (u.pn * HALF >= H16) {
; #pragma unroll
;             for (int ai = 0; ai < 2; ++ai)
; #pragma unroll
;                 for (int m = 0; m < 4; ++m) { unsigned char* rowp = (unsigned char*)O + (size_t)(row0 + ai * HALF + m * 16) * HROWB + H16 * 2 + (col0 - H16);
;                     float sa = 1.f; if constexpr (Q) sa = SA[row0 + ai * HALF + m * 16];
;                     const f32x4 g0 = deq(acc[ai][0][m][0], sa, cg0), g1 = deq(acc[ai][0][m][1], sa, cg1), u0 = deq(acc[ai][1][m][0], sa, cu0), u1 = deq(acc[ai][1][m][1], sa, cu1);
;                     float v[8];
; #pragma unroll
;                     for (int j = 0; j < 4; ++j) { v[j] = __builtin_amdgcn_fmed3f(silu_f(g0[j]) * u0[j] * 4.0f, -448.f, 448.f); v[4 + j] = __builtin_amdgcn_fmed3f(silu_f(g1[j]) * u1[j] * 4.0f, -448.f, 448.f); }
;                     int w0 = __builtin_amdgcn_cvt_pk_fp8_f32(v[0], v[1], 0, false); w0 = __builtin_amdgcn_cvt_pk_fp8_f32(v[2], v[3], w0, true);
;                     int w1 = __builtin_amdgcn_cvt_pk_fp8_f32(v[4], v[5], 0, false); w1 = __builtin_amdgcn_cvt_pk_fp8_f32(v[6], v[7], w1, true);
;                     typedef int i32x2 __attribute__((ext_vector_type(2)));
;                     *(i32x2*)rowp = (i32x2){w0, w1}; }
	v_exp_f32_e32 v108, v108
	v_exp_f32_e32 v109, v109
	v_add_f32_e32 v110, 1.0, v110
	v_rcp_f32_e32 v94, v94
	v_rcp_f32_e32 v102, v102
	v_rcp_f32_e32 v110, v110
	v_add_f32_e32 v108, 1.0, v108
	v_add_f32_e32 v109, 1.0, v109
	v_mul_f32_e32 v94, v117, v94
	v_mul_f32_e32 v102, v115, v102
	v_rcp_f32_e32 v108, v108
	v_rcp_f32_e32 v109, v109
	v_mul_f32_e32 v73, v73, v110
	v_mul_f32_e32 v94, v116, v94
	v_mul_f32_e32 v102, v114, v102
	v_mul_f32_e32 v72, v72, v73
	v_mul_f32_e32 v67, 4.0, v67
	v_mul_f32_e32 v94, 4.0, v94
	v_mul_f32_e32 v95, 4.0, v95
	v_mul_f32_e32 v102, 4.0, v102
	v_mul_f32_e32 v72, 4.0, v72
	v_med3_f32 v67, v67, s87, v160
	v_med3_f32 v94, v94, s87, v160
	v_med3_f32 v95, v95, s87, v160
	v_med3_f32 v102, v102, s87, v160
	v_med3_f32 v110, v72, s87, v160
	v_mov_b32_e32 v72, v193
	v_mov_b32_e32 v73, v193
	v_mul_f32_e32 v108, v113, v108
	v_mul_f32_e32 v109, v119, v109
	v_cvt_pk_fp8_f32 v72, v67, v95
	v_cvt_pk_fp8_f32 v73, v94, v102
	v_mul_f32_e32 v108, v112, v108
	v_mul_f32_e32 v109, v118, v109
	v_mul_f32_e32 v103, 4.0, v103
	v_mul_f32_e32 v108, 4.0, v108
	v_mul_f32_e32 v109, 4.0, v109
	v_med3_f32 v103, v103, s87, v160
	v_med3_f32 v108, v108, s87, v160
	v_med3_f32 v109, v109, s87, v160
	v_cvt_pk_fp8_f32 v72, v103, v109 op_sel:[0,0,1]
	v_cvt_pk_fp8_f32 v73, v108, v110 op_sel:[0,0,1]
	v_ashrrev_i32_e32 v67, 31, v66
	global_store_dwordx2 v[92:93], v[72:73], off offset:1536
	v_mad_i64_i32 v[72:73], s[4:5], v66, s86, v[58:59]
	v_lshl_add_u64 v[66:67], v[66:67], 2, s[92:93]
	v_mov_b32_e32 v66, v223
	v_lshl_add_u64 v[72:73], v[72:73], 0, v[156:157]
	s_nop 0
	v_pk_mul_f32 v[102:103], v[60:61], v[66:67] op_sel_hi:[1,0]
	s_nop 0
	v_pk_mul_f32 v[100:101], v[102:103], v[100:101]
	v_pk_mul_f32 v[102:103], v[34:35], v[66:67] op_sel_hi:[1,0]
	v_pk_mul_f32 v[94:95], v[32:33], v[66:67] op_sel_hi:[1,0]
	v_pk_mul_f32 v[98:99], v[102:103], v[98:99]
	v_pk_mul_f32 v[102:103], v[62:63], v[66:67] op_sel_hi:[1,0]
	v_pk_mul_f32 v[92:93], v[74:75], v[66:67] op_sel_hi:[1,0]
	v_pk_mul_f32 v[96:97], v[102:103], v[96:97]
	v_pk_mul_f32 v[102:103], v[20:21], v[66:67] op_sel_hi:[1,0]
	v_pk_mul_f32 v[94:95], v[94:95], v[104:105]
	v_pk_mul_f32 v[90:91], v[102:103], v[90:91]
	v_pk_mul_f32 v[102:103], v[56:57], v[66:67] op_sel_hi:[1,0]
	v_pk_mul_f32 v[66:67], v[22:23], v[66:67] op_sel_hi:[1,0]
	v_pk_mul_f32 v[92:93], v[92:93], v[106:107]
	v_pk_mul_f32 v[66:67], v[66:67], v[86:87]
	v_mul_f32_e32 v87, 0xbfb8aa3b, v95
	v_exp_f32_e32 v87, v87
	v_mul_f32_e32 v86, 0xbfb8aa3b, v93
	v_exp_f32_e32 v86, v86
	v_pk_mul_f32 v[88:89], v[102:103], v[88:89]
	v_add_f32_e32 v87, 1.0, v87
	v_rcp_f32_e32 v87, v87
	v_add_f32_e32 v86, 1.0, v86
	v_rcp_f32_e32 v86, v86
	v_mul_f32_e32 v87, v95, v87
	v_mul_f32_e32 v87, v94, v87
	v_mul_f32_e32 v87, 4.0, v87
	v_mul_f32_e32 v86, v93, v86
	v_med3_f32 v93, v87, s87, v160
	v_mul_f32_e32 v87, 0xbfb8aa3b, v91
	v_exp_f32_e32 v87, v87
	v_mul_f32_e32 v86, v92, v86
	v_mul_f32_e32 v86, 4.0, v86
	v_med3_f32 v92, v86, s87, v160
	v_add_f32_e32 v87, 1.0, v87
	v_rcp_f32_e32 v87, v87
	v_mul_f32_e32 v86, 0xbfb8aa3b, v97
	v_exp_f32_e32 v86, v86
	v_mul_f32_e32 v87, v91, v87
	v_mul_f32_e32 v91, 0xbfb8aa3b, v89
	v_exp_f32_e32 v91, v91
	v_mul_f32_e32 v87, v90, v87
	v_mul_f32_e32 v90, 0xbfb8aa3b, v101
	v_add_f32_e32 v86, 1.0, v86
	v_add_f32_e32 v91, 1.0, v91
	v_rcp_f32_e32 v91, v91
	v_exp_f32_e32 v90, v90
	v_rcp_f32_e32 v86, v86
	v_mul_f32_e32 v87, 4.0, v87
	v_mul_f32_e32 v89, v89, v91
	v_mul_f32_e32 v88, v88, v89
	v_mul_f32_e32 v89, 0xbfb8aa3b, v99
	v_exp_f32_e32 v89, v89
	v_add_f32_e32 v90, 1.0, v90
	v_mul_f32_e32 v86, v97, v86
	v_rcp_f32_e32 v90, v90
	v_add_f32_e32 v89, 1.0, v89
	v_rcp_f32_e32 v89, v89
	v_mul_f32_e32 v86, v96, v86
	v_mul_f32_e32 v86, 4.0, v86
	v_med3_f32 v86, v86, s87, v160
	v_mul_f32_e32 v89, v99, v89
	v_mul_f32_e32 v89, v98, v89
	v_mul_f32_e32 v89, 4.0, v89
	v_med3_f32 v91, v89, s87, v160
	v_mul_f32_e32 v89, 0xbfb8aa3b, v67
	v_exp_f32_e32 v89, v89
	v_med3_f32 v87, v87, s87, v160
	v_mul_f32_e32 v90, v101, v90
	v_mul_f32_e32 v90, v100, v90
	v_add_f32_e32 v89, 1.0, v89
	v_rcp_f32_e32 v89, v89
	v_mul_f32_e32 v90, 4.0, v90
	v_mul_f32_e32 v88, 4.0, v88
	v_med3_f32 v90, v90, s87, v160
	v_mul_f32_e32 v67, v67, v89
	v_mul_f32_e32 v66, v66, v67
	v_mul_f32_e32 v66, 4.0, v66
	v_med3_f32 v89, v66, s87, v160
	v_mov_b32_e32 v66, v193
	v_mov_b32_e32 v67, v193
	v_cvt_pk_fp8_f32 v66, v92, v93
	v_cvt_pk_fp8_f32 v67, v86, v87
	v_med3_f32 v88, v88, s87, v160
	v_cvt_pk_fp8_f32 v66, v90, v91 op_sel:[0,0,1]
	v_cvt_pk_fp8_f32 v67, v88, v89 op_sel:[0,0,1]
	global_store_dwordx2 v[72:73], v[66:67], off offset:1536
	v_mov_b32_e32 v72, v224
	v_mad_i64_i32 v[66:67], s[4:5], v155, s86, v[58:59]
	v_lshl_add_u64 v[66:67], v[66:67], 0, v[156:157]
	s_nop 0
	v_pk_mul_f32 v[86:87], v[74:75], v[72:73] op_sel_hi:[1,0]
	s_nop 0
	v_pk_mul_f32 v[84:85], v[86:87], v[84:85]
	v_pk_mul_f32 v[86:87], v[32:33], v[72:73] op_sel_hi:[1,0]
	s_nop 0
	v_pk_mul_f32 v[82:83], v[86:87], v[82:83]
	v_pk_mul_f32 v[86:87], v[60:61], v[72:73] op_sel_hi:[1,0]
	s_nop 0
	v_pk_mul_f32 v[80:81], v[86:87], v[80:81]
	v_pk_mul_f32 v[86:87], v[34:35], v[72:73] op_sel_hi:[1,0]
	s_nop 0
	v_pk_mul_f32 v[78:79], v[86:87], v[78:79]
	v_pk_mul_f32 v[86:87], v[62:63], v[72:73] op_sel_hi:[1,0]
	s_nop 0
	v_pk_mul_f32 v[76:77], v[86:87], v[76:77]
	v_pk_mul_f32 v[86:87], v[20:21], v[72:73] op_sel_hi:[1,0]
	s_nop 0
	v_pk_mul_f32 v[70:71], v[86:87], v[70:71]
	v_pk_mul_f32 v[86:87], v[56:57], v[72:73] op_sel_hi:[1,0]
	s_nop 0
	v_pk_mul_f32 v[86:87], v[86:87], v[68:69]
	v_pk_mul_f32 v[68:69], v[22:23], v[72:73] op_sel_hi:[1,0]
	s_nop 0
	v_pk_mul_f32 v[64:65], v[68:69], v[64:65]
	v_mul_f32_e32 v69, 0xbfb8aa3b, v83
	v_exp_f32_e32 v69, v69
; __device__ __forceinline__ float silu_f(float x) { return x * __builtin_amdgcn_rcpf(1.0f + __builtin_amdgcn_exp2f(-1.4426950408889634f * x)); }
;     static __device__ __forceinline__ f32x4 deq(const f32x4 a, const float sa, const f32x4 cm) { if constexpr (!Q) return a; else { const i32x4 i = __builtin_bit_cast(i32x4, a); return (f32x4){(float)i[0] * (sa * cm[0]), (float)i[1] * (sa * cm[1]), (float)i[2] * (sa * cm[2]), (float)i[3] * (sa * cm[ ...
;     __device__ __forceinline__ void operator()(const f32x4 (&acc)[2][2][4][2], const Unit& u, int wr, int wc, int fr, int fq) const {
;     ...
;         if (u.pn * HALF >= H16) {
; #pragma unroll
;             for (int ai = 0; ai < 2; ++ai)
; #pragma unroll
;                 for (int m = 0; m < 4; ++m) { unsigned char* rowp = (unsigned char*)O + (size_t)(row0 + ai * HALF + m * 16) * HROWB + H16 * 2 + (col0 - H16);
;                     float sa = 1.f; if constexpr (Q) sa = SA[row0 + ai * HALF + m * 16];
;                     const f32x4 g0 = deq(acc[ai][0][m][0], sa, cg0), g1 = deq(acc[ai][0][m][1], sa, cg1), u0 = deq(acc[ai][1][m][0], sa, cu0), u1 = deq(acc[ai][1][m][1], sa, cu1);
;                     float v[8];
; #pragma unroll
;                     for (int j = 0; j < 4; ++j) { v[j] = __builtin_amdgcn_fmed3f(silu_f(g0[j]) * u0[j] * 4.0f, -448.f, 448.f); v[4 + j] = __builtin_amdgcn_fmed3f(silu_f(g1[j]) * u1[j] * 4.0f, -448.f, 448.f); }
;                     int w0 = __builtin_amdgcn_cvt_pk_fp8_f32(v[0], v[1], 0, false); w0 = __builtin_amdgcn_cvt_pk_fp8_f32(v[2], v[3], w0, true);
;                     int w1 = __builtin_amdgcn_cvt_pk_fp8_f32(v[4], v[5], 0, false); w1 = __builtin_amdgcn_cvt_pk_fp8_f32(v[6], v[7], w1, true);
;                     typedef int i32x2 __attribute__((ext_vector_type(2)));
;                     *(i32x2*)rowp = (i32x2){w0, w1}; }
	v_mul_f32_e32 v68, 0xbfb8aa3b, v85
	v_exp_f32_e32 v68, v68
	v_add_f32_e32 v69, 1.0, v69
	v_rcp_f32_e32 v69, v69
	v_add_f32_e32 v68, 1.0, v68
	v_rcp_f32_e32 v68, v68
	v_mul_f32_e32 v69, v83, v69
	v_mul_f32_e32 v69, v82, v69
	v_mul_f32_e32 v69, 4.0, v69
	v_med3_f32 v73, v69, s87, v160
	v_mul_f32_e32 v69, 0xbfb8aa3b, v71
	v_exp_f32_e32 v69, v69
	v_mul_f32_e32 v68, v85, v68
	v_mul_f32_e32 v68, v84, v68
	v_mul_f32_e32 v68, 4.0, v68
	v_add_f32_e32 v69, 1.0, v69
	v_rcp_f32_e32 v69, v69
	v_med3_f32 v72, v68, s87, v160
	v_mul_f32_e32 v68, 0xbfb8aa3b, v77
	v_exp_f32_e32 v68, v68
	v_mul_f32_e32 v69, v71, v69
	v_mul_f32_e32 v71, 0xbfb8aa3b, v79
	v_exp_f32_e32 v71, v71
	v_mul_f32_e32 v69, v70, v69
	v_mul_f32_e32 v70, 0xbfb8aa3b, v81
	v_exp_f32_e32 v70, v70
	v_add_f32_e32 v71, 1.0, v71
	v_rcp_f32_e32 v71, v71
	v_add_f32_e32 v68, 1.0, v68
	v_rcp_f32_e32 v68, v68
	v_add_f32_e32 v70, 1.0, v70
	v_rcp_f32_e32 v70, v70
	v_mul_f32_e32 v71, v79, v71
	v_mul_f32_e32 v71, v78, v71
	v_mul_f32_e32 v71, 4.0, v71
	v_mul_f32_e32 v68, v77, v68
	v_med3_f32 v77, v71, s87, v160
	v_mul_f32_e32 v71, 0xbfb8aa3b, v65
	v_mul_f32_e32 v70, v81, v70
	v_exp_f32_e32 v71, v71
	v_mul_f32_e32 v70, v80, v70
	v_mul_f32_e32 v70, 4.0, v70
	v_mul_f32_e32 v68, v76, v68
	v_med3_f32 v76, v70, s87, v160
	v_mul_f32_e32 v70, 0xbfb8aa3b, v87
	v_exp_f32_e32 v70, v70
	v_add_f32_e32 v71, 1.0, v71
	v_rcp_f32_e32 v71, v71
	v_mul_f32_e32 v68, 4.0, v68
	v_add_f32_e32 v70, 1.0, v70
	v_rcp_f32_e32 v70, v70
	v_mul_f32_e32 v65, v65, v71
	v_mul_f32_e32 v64, v64, v65
	v_mul_f32_e32 v69, 4.0, v69
	v_mul_f32_e32 v64, 4.0, v64
	v_med3_f32 v68, v68, s87, v160
	v_med3_f32 v69, v69, s87, v160
	v_med3_f32 v71, v64, s87, v160
	v_mov_b32_e32 v64, v193
	v_mov_b32_e32 v65, v193
	v_mul_f32_e32 v70, v87, v70
	v_cvt_pk_fp8_f32 v64, v72, v73
	v_cvt_pk_fp8_f32 v65, v68, v69
	v_mul_f32_e32 v70, v86, v70
	v_mul_f32_e32 v70, 4.0, v70
	v_med3_f32 v70, v70, s87, v160
	v_cvt_pk_fp8_f32 v64, v76, v77 op_sel:[0,0,1]
	v_cvt_pk_fp8_f32 v65, v70, v71 op_sel:[0,0,1]
	v_cvt_f32_i32_e32 v69, v52
	v_cvt_f32_i32_e32 v52, v49
	v_cvt_f32_i32_e32 v68, v48
	global_store_dwordx2 v[66:67], v[64:65], off offset:1536
	v_mov_b32_e32 v66, v225
	v_add_u32_e32 v64, 0x90, v154
	v_mad_i64_i32 v[64:65], s[4:5], v64, s86, v[58:59]
	v_lshl_add_u64 v[64:65], v[64:65], 0, v[156:157]
	s_nop 0
	v_pk_mul_f32 v[48:49], v[32:33], v[66:67] op_sel_hi:[1,0]
	s_nop 0
	v_pk_mul_f32 v[48:49], v[48:49], v[52:53]
	v_cvt_f32_i32_e32 v53, v54
	v_cvt_f32_i32_e32 v54, v51
	v_cvt_f32_i32_e32 v52, v50
	v_pk_mul_f32 v[50:51], v[34:35], v[66:67] op_sel_hi:[1,0]
	v_pk_mul_f32 v[70:71], v[74:75], v[66:67] op_sel_hi:[1,0]
	v_pk_mul_f32 v[50:51], v[50:51], v[54:55]
	v_cvt_f32_i32_e32 v55, v44
	v_cvt_f32_i32_e32 v44, v41
	v_cvt_f32_i32_e32 v54, v40
	v_pk_mul_f32 v[40:41], v[20:21], v[66:67] op_sel_hi:[1,0]
	v_pk_mul_f32 v[68:69], v[70:71], v[68:69]
	v_pk_mul_f32 v[40:41], v[40:41], v[44:45]
	v_cvt_f32_i32_e32 v45, v46
	v_cvt_f32_i32_e32 v46, v43
	v_cvt_f32_i32_e32 v44, v42
	v_pk_mul_f32 v[42:43], v[22:23], v[66:67] op_sel_hi:[1,0]
	v_pk_mul_f32 v[70:71], v[60:61], v[66:67] op_sel_hi:[1,0]
	v_pk_mul_f32 v[46:47], v[42:43], v[46:47]
	v_mul_f32_e32 v43, 0xbfb8aa3b, v49
	v_exp_f32_e32 v43, v43
	v_pk_mul_f32 v[52:53], v[70:71], v[52:53]
	v_pk_mul_f32 v[70:71], v[62:63], v[66:67] op_sel_hi:[1,0]
	v_mul_f32_e32 v42, 0xbfb8aa3b, v69
	v_add_f32_e32 v43, 1.0, v43
	v_rcp_f32_e32 v43, v43
	v_pk_mul_f32 v[54:55], v[70:71], v[54:55]
	v_pk_mul_f32 v[70:71], v[56:57], v[66:67] op_sel_hi:[1,0]
	v_exp_f32_e32 v42, v42
	v_mul_f32_e32 v43, v49, v43
	v_mul_f32_e32 v43, v48, v43
	v_mul_f32_e32 v43, 4.0, v43
	v_med3_f32 v48, v43, s87, v160
	v_mul_f32_e32 v43, 0xbfb8aa3b, v41
	v_exp_f32_e32 v43, v43
	v_pk_mul_f32 v[44:45], v[70:71], v[44:45]
	v_add_f32_e32 v42, 1.0, v42
	v_rcp_f32_e32 v42, v42
	v_add_f32_e32 v43, 1.0, v43
	v_rcp_f32_e32 v43, v43
	v_mul_f32_e32 v42, v69, v42
	v_mul_f32_e32 v42, v68, v42
	v_mul_f32_e32 v41, v41, v43
	v_mul_f32_e32 v40, v40, v41
	v_mul_f32_e32 v40, 4.0, v40
	v_med3_f32 v43, v40, s87, v160
	v_mul_f32_e32 v40, 0xbfb8aa3b, v53
	v_exp_f32_e32 v40, v40
	v_mul_f32_e32 v42, 4.0, v42
	v_med3_f32 v66, v42, s87, v160
	v_mul_f32_e32 v42, 0xbfb8aa3b, v55
	v_add_f32_e32 v40, 1.0, v40
	v_rcp_f32_e32 v40, v40
	v_exp_f32_e32 v42, v42
	v_mul_f32_e32 v40, v53, v40
	v_mul_f32_e32 v40, v52, v40
	v_mul_f32_e32 v40, 4.0, v40
	v_med3_f32 v41, v40, s87, v160
	v_mul_f32_e32 v40, 0xbfb8aa3b, v45
	v_exp_f32_e32 v40, v40
	v_add_f32_e32 v42, 1.0, v42
	v_rcp_f32_e32 v42, v42
	v_add_f32_e32 v40, 1.0, v40
	v_rcp_f32_e32 v40, v40
	v_mul_f32_e32 v42, v55, v42
	v_mul_f32_e32 v42, v54, v42
	v_mul_f32_e32 v42, 4.0, v42
	v_mul_f32_e32 v40, v45, v40
	v_mul_f32_e32 v40, v44, v40
	v_mul_f32_e32 v40, 4.0, v40
	v_med3_f32 v44, v40, s87, v160
	v_mul_f32_e32 v40, 0xbfb8aa3b, v51
	v_exp_f32_e32 v40, v40
	v_med3_f32 v42, v42, s87, v160
	v_add_f32_e32 v40, 1.0, v40
	v_rcp_f32_e32 v40, v40
	s_nop 0
	v_mul_f32_e32 v40, v51, v40
	v_mul_f32_e32 v40, v50, v40
	v_mul_f32_e32 v40, 4.0, v40
	v_med3_f32 v49, v40, s87, v160
	v_mul_f32_e32 v40, 0xbfb8aa3b, v47
	v_exp_f32_e32 v40, v40
	s_nop 0
	v_add_f32_e32 v40, 1.0, v40
	v_rcp_f32_e32 v40, v40
	s_nop 0
	v_mul_f32_e32 v40, v47, v40
	v_mul_f32_e32 v40, v46, v40
	v_mul_f32_e32 v40, 4.0, v40
	v_med3_f32 v45, v40, s87, v160
	v_mov_b32_e32 v40, v193
	v_cvt_pk_fp8_f32 v40, v66, v48
	v_cvt_pk_fp8_f32 v40, v41, v49 op_sel:[0,0,1]
	v_mov_b32_e32 v41, v193
	v_cvt_pk_fp8_f32 v41, v42, v43
	v_cvt_pk_fp8_f32 v41, v44, v45 op_sel:[0,0,1]
	v_cvt_f32_i32_e32 v45, v36
	v_cvt_f32_i32_e32 v36, v29
	v_cvt_f32_i32_e32 v44, v28
	global_store_dwordx2 v[64:65], v[40:41], off offset:1536
	v_mov_b32_e32 v42, v226
; __device__ __forceinline__ float silu_f(float x) { return x * __builtin_amdgcn_rcpf(1.0f + __builtin_amdgcn_exp2f(-1.4426950408889634f * x)); }
;     static __device__ __forceinline__ f32x4 deq(const f32x4 a, const float sa, const f32x4 cm) { if constexpr (!Q) return a; else { const i32x4 i = __builtin_bit_cast(i32x4, a); return (f32x4){(float)i[0] * (sa * cm[0]), (float)i[1] * (sa * cm[1]), (float)i[2] * (sa * cm[2]), (float)i[3] * (sa * cm[3])}; } }
;     __device__ __forceinline__ void operator()(const f32x4 (&acc)[2][2][4][2], const Unit& u, int wr, int wc, int fr, int fq) const {
;     ...
;         if (u.pn * HALF >= H16) {
; #pragma unroll
;             for (int ai = 0; ai < 2; ++ai)
; #pragma unroll
;                 for (int m = 0; m < 4; ++m) { unsigned char* rowp = (unsigned char*)O + (size_t)(row0 + ai * HALF + m * 16) * HROWB + H16 * 2 + (col0 - H16);
;                     float sa = 1.f; if constexpr (Q) sa = SA[row0 + ai * HALF + m * 16];
;                     const f32x4 g0 = deq(acc[ai][0][m][0], sa, cg0), g1 = deq(acc[ai][0][m][1], sa, cg1), u0 = deq(acc[ai][1][m][0], sa, cu0), u1 = deq(acc[ai][1][m][1], sa, cu1);
;                     float v[8];
; #pragma unroll
;                     for (int j = 0; j < 4; ++j) { v[j] = __builtin_amdgcn_fmed3f(silu_f(g0[j]) * u0[j] * 4.0f, -448.f, 448.f); v[4 + j] = __builtin_amdgcn_fmed3f(silu_f(g1[j]) * u1[j] * 4.0f, -448.f, 448.f); }
;                     int w0 = __builtin_amdgcn_cvt_pk_fp8_f32(v[0], v[1], 0, false); w0 = __builtin_amdgcn_cvt_pk_fp8_f32(v[2], v[3], w0, true);
;                     int w1 = __builtin_amdgcn_cvt_pk_fp8_f32(v[4], v[5], 0, false); w1 = __builtin_amdgcn_cvt_pk_fp8_f32(v[6], v[7], w1, true);
;                     typedef int i32x2 __attribute__((ext_vector_type(2)));
;                     *(i32x2*)rowp = (i32x2){w0, w1}; }
	v_add_u32_e32 v40, 0xa0, v154
	v_mad_i64_i32 v[40:41], s[4:5], v40, s86, v[58:59]
	v_lshl_add_u64 v[40:41], v[40:41], 0, v[156:157]
	s_nop 0
	v_pk_mul_f32 v[28:29], v[32:33], v[42:43] op_sel_hi:[1,0]
	s_nop 0
	v_pk_mul_f32 v[28:29], v[28:29], v[36:37]
	v_cvt_f32_i32_e32 v37, v38
	v_cvt_f32_i32_e32 v38, v31
	v_cvt_f32_i32_e32 v36, v30
	v_pk_mul_f32 v[30:31], v[34:35], v[42:43] op_sel_hi:[1,0]
	v_pk_mul_f32 v[46:47], v[74:75], v[42:43] op_sel_hi:[1,0]
	v_pk_mul_f32 v[30:31], v[30:31], v[38:39]
	v_cvt_f32_i32_e32 v39, v24
	v_cvt_f32_i32_e32 v24, v17
	v_cvt_f32_i32_e32 v38, v16
	v_pk_mul_f32 v[16:17], v[20:21], v[42:43] op_sel_hi:[1,0]
	v_pk_mul_f32 v[44:45], v[46:47], v[44:45]
	v_pk_mul_f32 v[16:17], v[16:17], v[24:25]
	v_cvt_f32_i32_e32 v25, v26
	v_cvt_f32_i32_e32 v26, v19
	v_cvt_f32_i32_e32 v24, v18
	v_pk_mul_f32 v[18:19], v[22:23], v[42:43] op_sel_hi:[1,0]
	v_pk_mul_f32 v[46:47], v[60:61], v[42:43] op_sel_hi:[1,0]
	v_pk_mul_f32 v[26:27], v[18:19], v[26:27]
	v_mul_f32_e32 v19, 0xbfb8aa3b, v29
	v_exp_f32_e32 v19, v19
	v_pk_mul_f32 v[36:37], v[46:47], v[36:37]
	v_pk_mul_f32 v[46:47], v[62:63], v[42:43] op_sel_hi:[1,0]
	v_mul_f32_e32 v18, 0xbfb8aa3b, v45
	v_add_f32_e32 v19, 1.0, v19
	v_rcp_f32_e32 v19, v19
	v_pk_mul_f32 v[38:39], v[46:47], v[38:39]
	v_pk_mul_f32 v[46:47], v[56:57], v[42:43] op_sel_hi:[1,0]
	v_exp_f32_e32 v18, v18
	v_mul_f32_e32 v19, v29, v19
	v_mul_f32_e32 v19, v28, v19
	v_mul_f32_e32 v19, 4.0, v19
	v_med3_f32 v28, v19, s87, v160
	v_mul_f32_e32 v19, 0xbfb8aa3b, v17
	v_exp_f32_e32 v19, v19
	v_pk_mul_f32 v[24:25], v[46:47], v[24:25]
	v_add_f32_e32 v18, 1.0, v18
	v_rcp_f32_e32 v18, v18
	v_add_f32_e32 v19, 1.0, v19
	v_rcp_f32_e32 v19, v19
	v_mul_f32_e32 v18, v45, v18
	v_mul_f32_e32 v18, v44, v18
	v_mul_f32_e32 v17, v17, v19
	v_mul_f32_e32 v16, v16, v17
	v_mul_f32_e32 v16, 4.0, v16
	v_med3_f32 v19, v16, s87, v160
	v_mul_f32_e32 v16, 0xbfb8aa3b, v37
	v_exp_f32_e32 v16, v16
	v_mul_f32_e32 v18, 4.0, v18
	v_med3_f32 v42, v18, s87, v160
	v_mul_f32_e32 v18, 0xbfb8aa3b, v39
	v_add_f32_e32 v16, 1.0, v16
	v_rcp_f32_e32 v16, v16
	v_exp_f32_e32 v18, v18
	v_mul_f32_e32 v16, v37, v16
	v_mul_f32_e32 v16, v36, v16
	v_mul_f32_e32 v16, 4.0, v16
	v_med3_f32 v17, v16, s87, v160
	v_mul_f32_e32 v16, 0xbfb8aa3b, v25
	v_exp_f32_e32 v16, v16
	v_add_f32_e32 v18, 1.0, v18
	v_rcp_f32_e32 v18, v18
	v_add_f32_e32 v16, 1.0, v16
	v_rcp_f32_e32 v16, v16
	v_mul_f32_e32 v18, v39, v18
	v_mul_f32_e32 v18, v38, v18
	v_mul_f32_e32 v18, 4.0, v18
	v_mul_f32_e32 v16, v25, v16
	v_mul_f32_e32 v16, v24, v16
	v_mul_f32_e32 v16, 4.0, v16
	v_med3_f32 v24, v16, s87, v160
	v_mul_f32_e32 v16, 0xbfb8aa3b, v31
	v_exp_f32_e32 v16, v16
	v_med3_f32 v18, v18, s87, v160
	v_add_f32_e32 v16, 1.0, v16
	v_rcp_f32_e32 v16, v16
	s_nop 0
	v_mul_f32_e32 v16, v31, v16
	v_mul_f32_e32 v16, v30, v16
	v_mul_f32_e32 v16, 4.0, v16
	v_med3_f32 v29, v16, s87, v160
	v_mul_f32_e32 v16, 0xbfb8aa3b, v27
	v_exp_f32_e32 v16, v16
	s_nop 0
	v_add_f32_e32 v16, 1.0, v16
	v_rcp_f32_e32 v16, v16
	s_nop 0
	v_mul_f32_e32 v16, v27, v16
	v_mul_f32_e32 v16, v26, v16
	v_mul_f32_e32 v16, 4.0, v16
	v_med3_f32 v25, v16, s87, v160
	v_mov_b32_e32 v16, v193
	v_cvt_pk_fp8_f32 v16, v42, v28
	v_cvt_pk_fp8_f32 v16, v17, v29 op_sel:[0,0,1]
	v_mov_b32_e32 v17, v193
	v_cvt_pk_fp8_f32 v17, v18, v19
	v_cvt_pk_fp8_f32 v17, v24, v25 op_sel:[0,0,1]
	v_cvt_f32_i32_e32 v25, v12
	v_cvt_f32_i32_e32 v12, v9
	v_cvt_f32_i32_e32 v24, v8
	global_store_dwordx2 v[40:41], v[16:17], off offset:1536
	v_mov_b32_e32 v18, v227
	v_add_u32_e32 v16, 0xb0, v154
	v_mad_i64_i32 v[16:17], s[4:5], v16, s86, v[58:59]
	v_lshl_add_u64 v[16:17], v[16:17], 0, v[156:157]
	s_nop 0
	v_pk_mul_f32 v[8:9], v[32:33], v[18:19] op_sel_hi:[1,0]
	s_nop 0
	v_pk_mul_f32 v[8:9], v[8:9], v[12:13]
	v_cvt_f32_i32_e32 v13, v14
	v_cvt_f32_i32_e32 v14, v11
	v_cvt_f32_i32_e32 v12, v10
	v_pk_mul_f32 v[10:11], v[34:35], v[18:19] op_sel_hi:[1,0]
	v_pk_mul_f32 v[26:27], v[74:75], v[18:19] op_sel_hi:[1,0]
	v_pk_mul_f32 v[10:11], v[10:11], v[14:15]
	v_cvt_f32_i32_e32 v15, v4
	v_cvt_f32_i32_e32 v4, v1
	v_cvt_f32_i32_e32 v14, v0
	v_pk_mul_f32 v[0:1], v[20:21], v[18:19] op_sel_hi:[1,0]
	v_pk_mul_f32 v[24:25], v[26:27], v[24:25]
	v_pk_mul_f32 v[0:1], v[0:1], v[4:5]
	v_cvt_f32_i32_e32 v5, v6
	v_cvt_f32_i32_e32 v6, v3
	v_cvt_f32_i32_e32 v4, v2
	v_pk_mul_f32 v[2:3], v[22:23], v[18:19] op_sel_hi:[1,0]
	v_pk_mul_f32 v[26:27], v[60:61], v[18:19] op_sel_hi:[1,0]
	v_pk_mul_f32 v[6:7], v[2:3], v[6:7]
	v_mul_f32_e32 v3, 0xbfb8aa3b, v9
	v_exp_f32_e32 v3, v3
	v_pk_mul_f32 v[12:13], v[26:27], v[12:13]
	v_pk_mul_f32 v[20:21], v[56:57], v[18:19] op_sel_hi:[1,0]
	v_mul_f32_e32 v2, 0xbfb8aa3b, v25
	v_add_f32_e32 v3, 1.0, v3
	v_rcp_f32_e32 v3, v3
	v_pk_mul_f32 v[4:5], v[20:21], v[4:5]
	v_exp_f32_e32 v2, v2
	v_pk_mul_f32 v[26:27], v[62:63], v[18:19] op_sel_hi:[1,0]
	v_mul_f32_e32 v3, v9, v3
	v_mul_f32_e32 v3, v8, v3
	v_mul_f32_e32 v3, 4.0, v3
	v_med3_f32 v8, v3, s87, v160
	v_mul_f32_e32 v3, 0xbfb8aa3b, v1
	v_exp_f32_e32 v3, v3
	v_add_f32_e32 v2, 1.0, v2
	v_rcp_f32_e32 v2, v2
	v_pk_mul_f32 v[14:15], v[26:27], v[14:15]
	v_add_f32_e32 v3, 1.0, v3
	v_rcp_f32_e32 v3, v3
	v_mul_f32_e32 v2, v25, v2
	v_mul_f32_e32 v2, v24, v2
	v_mul_f32_e32 v2, 4.0, v2
	v_mul_f32_e32 v1, v1, v3
	v_mul_f32_e32 v0, v0, v1
	v_mul_f32_e32 v0, 4.0, v0
	v_med3_f32 v3, v0, s87, v160
	v_mul_f32_e32 v0, 0xbfb8aa3b, v13
	v_exp_f32_e32 v0, v0
	v_med3_f32 v18, v2, s87, v160
	v_mul_f32_e32 v2, 0xbfb8aa3b, v15
	v_exp_f32_e32 v2, v2
	v_add_f32_e32 v0, 1.0, v0
	v_rcp_f32_e32 v0, v0
	v_add_f32_e32 v2, 1.0, v2
	v_rcp_f32_e32 v2, v2
	v_mul_f32_e32 v0, v13, v0
	v_mul_f32_e32 v0, v12, v0
	v_mul_f32_e32 v0, 4.0, v0
	v_med3_f32 v1, v0, s87, v160
	v_mul_f32_e32 v0, 0xbfb8aa3b, v5
	v_exp_f32_e32 v0, v0
	v_mul_f32_e32 v2, v15, v2
	v_mul_f32_e32 v2, v14, v2
	v_mul_f32_e32 v2, 4.0, v2
	v_add_f32_e32 v0, 1.0, v0
	v_rcp_f32_e32 v0, v0
	v_med3_f32 v2, v2, s87, v160
	v_mul_f32_e32 v0, v5, v0
	v_mul_f32_e32 v0, v4, v0
	v_mul_f32_e32 v0, 4.0, v0
	v_med3_f32 v4, v0, s87, v160
	v_mul_f32_e32 v0, 0xbfb8aa3b, v11
	v_exp_f32_e32 v0, v0
	s_nop 0
	v_add_f32_e32 v0, 1.0, v0
	v_rcp_f32_e32 v0, v0
	s_nop 0
	v_mul_f32_e32 v0, v11, v0
	v_mul_f32_e32 v0, v10, v0
	v_mul_f32_e32 v0, 4.0, v0
	v_med3_f32 v9, v0, s87, v160
	v_mul_f32_e32 v0, 0xbfb8aa3b, v7
	v_exp_f32_e32 v0, v0
	s_nop 0
	v_add_f32_e32 v0, 1.0, v0
	v_rcp_f32_e32 v0, v0
	s_nop 0
	v_mul_f32_e32 v0, v7, v0
	v_mul_f32_e32 v0, v6, v0
	v_mul_f32_e32 v0, 4.0, v0
	v_med3_f32 v5, v0, s87, v160
	v_mov_b32_e32 v0, v193
	v_cvt_pk_fp8_f32 v0, v18, v8
	v_cvt_pk_fp8_f32 v0, v1, v9 op_sel:[0,0,1]
	v_mov_b32_e32 v1, v193
	v_cvt_pk_fp8_f32 v1, v2, v3
	v_cvt_pk_fp8_f32 v1, v4, v5 op_sel:[0,0,1]
	global_store_dwordx2 v[16:17], v[0:1], off offset:1536
	s_andn2_b64 vcc, exec, s[40:41]
	s_mov_b64 s[24:25], -1
	s_cbranch_vccnz .LBB0_548
